# GEMM MFMA phases: k-half-major group order (both row halves on the first k half, then both on the second; dependent MFMAs 16 apart)
# speedup vs baseline: 1.0089x; 1.0040x over previous
; #define PG8_STAGE(bufoff, gbase, voff) do { _Pragma("unroll") for (int _i = 0; _i < 2; ++_i) \
;         __builtin_amdgcn_global_load_lds((const unsigned*)((const char*)(gbase) + (voff)[_i]), (LAS unsigned*)(lds + (bufoff) + ldsw + _i * 8192), 16, 0, 0); } while (0)
; #define PG8_LDA(dst, b, h) do { _Pragma("unroll") for (int m = 0; m < 4; ++m) _Pragma("unroll") for (int k = 0; k < 2; ++k) dst[m][k] = *(const LAS bf16x8*)(lds + PG8_SA(b, h) + aoff + m * 2048 + k * 1024); } while (0)
; #define PG8_LDB(dst, b, h) do { _Pragma("unroll") for (int n = 0; n < 2; ++n) _Pragma("unroll") for (int k = 0; k < 2; ++k) dst[n][k] = *(const LAS bf16x8*)(lds + PG8_SB(b, h) + boff + n * 2048 + k * 1024); } while (0)
; #define PG8_MMA(ai, bj, At, Bt) do { __builtin_amdgcn_s_setprio(1); _Pragma("unroll") for (int m = 0; m < 4; ++m) _Pragma("unroll") for (int n = 0; n < 2; ++n) _Pragma("unroll") for (int k = 0; k < 2; ++k) \
;         acc[ai][bj][m][n] = __builtin_amdgcn_mfma_f32_16x16x32_bf16(Bt[n][k], At[m][k], acc[ai][bj][m][n], 0, 0, 0); __builtin_amdgcn_s_setprio(0); } while (0)
; #define PG8_WAIT_V(n) asm volatile("s_waitcnt vmcnt(" #n ")" ::: "memory")
; #define PG8_WAIT_L(n) asm volatile("s_waitcnt lgkmcnt(" #n ")" ::: "memory")
; #define PG8_BAR __builtin_amdgcn_s_barrier()
; #define PG8_SCHED __builtin_amdgcn_sched_barrier(0)
; template <class Epi>
; __device__ __forceinline__ void gemm_phase(LAS unsigned char* lds, const Gemm g, const StaticOrder& S, const Epi& E) {
;     ...
;         for (int t = 0; t < nt; t += 2) {
;             const bool last = (t == nt - 2);
;             const char* a1 = cA + (size_t)(t + 1) * kstep;
;             const char* a2 = last ? nA : cA + (size_t)(t + 2) * kstep; const char* b2 = last ? nB : cB + (size_t)(t + 2) * kstep;
;             const char* a3 = a2 + kstep; const char* b3 = b2 + kstep;
;             PG8_LDB(B0, 0, 0); PG8_LDB(B1, 0, 1); PG8_SCHED; PG8_LDA(At, 0, 0); PG8_STAGE(PG8_SA(1, 1), a1 + hA, voffA);
;             PG8_WAIT_V(8); PG8_WAIT_L(0); PG8_BAR; PG8_MMA(0, 0, At, B0); PG8_MMA(0, 1, At, B1); PG8_BAR; PG8_SCHED;
;             PG8_LDA(At, 0, 1); PG8_STAGE(PG8_SB(0, 0), b2, voffB); PG8_STAGE(PG8_SB(0, 1), b2 + hB, voffB); PG8_STAGE(PG8_SA(0, 0), a2, voffA);
;             PG8_WAIT_V(8); PG8_WAIT_L(0); PG8_BAR; PG8_MMA(1, 0, At, B0); PG8_MMA(1, 1, At, B1); PG8_BAR; PG8_SCHED;
.LBB0_132:
	s_add_u32 s34, s8, 0xfffc0080
	s_addc_u32 s35, s9, -1
	s_add_i32 s42, 0, 0x10000
	s_cmp_eq_u32 s41, 12
	s_cselect_b32 s37, s7, s35
	s_cselect_b32 s36, s27, s34
	v_add_u32_e32 v153, s42, v139
	s_cselect_b32 s35, s25, s40
	s_cselect_b32 s34, s38, s39
	s_add_i32 s44, 0, 0x14000
	ds_read_b128 v[166:169], v153
	ds_read_b128 v[170:173], v153 offset:1024
	ds_read_b128 v[174:177], v153 offset:2048
	ds_read_b128 v[182:185], v153 offset:3072
	v_add_u32_e32 v153, s44, v139
	ds_read_b128 v[186:189], v153
	ds_read_b128 v[190:193], v153 offset:1024
	ds_read_b128 v[194:197], v153 offset:2048
	ds_read_b128 v[198:201], v153 offset:3072
	v_lshl_add_u64 v[178:179], s[8:9], 0, v[162:163]
	s_add_i32 m0, s19, 0xc000
	ds_read_b128 v[202:205], v149
	ds_read_b128 v[206:209], v149 offset:1024
	ds_read_b128 v[210:213], v149 offset:2048
	ds_read_b128 v[214:217], v149 offset:3072
	ds_read_b128 v[218:221], v149 offset:4096
	ds_read_b128 v[232:235], v149 offset:5120
	ds_read_b128 v[236:239], v149 offset:6144
	ds_read_b128 v[240:243], v149 offset:7168
	global_load_lds_dwordx4 v[178:179], off
	v_lshl_add_u64 v[178:179], s[8:9], 0, v[164:165]
	s_add_i32 m0, s19, 0xe000
	s_nop 0
	global_load_lds_dwordx4 v[178:179], off
	s_waitcnt vmcnt(8)
	s_waitcnt lgkmcnt(0)
	s_barrier
	s_setprio 1
	v_mfma_f32_16x16x32_bf16 v[126:129], v[166:169], v[202:205], v[126:129]
	v_mfma_f32_16x16x32_bf16 v[122:125], v[174:177], v[202:205], v[122:125]
	v_mfma_f32_16x16x32_bf16 v[110:113], v[166:169], v[210:213], v[110:113]
	v_mfma_f32_16x16x32_bf16 v[106:109], v[174:177], v[210:213], v[106:109]
	v_mfma_f32_16x16x32_bf16 v[94:97], v[166:169], v[218:221], v[94:97]
	v_mfma_f32_16x16x32_bf16 v[90:93], v[174:177], v[218:221], v[90:93]
	v_mfma_f32_16x16x32_bf16 v[78:81], v[166:169], v[236:239], v[78:81]
	v_mfma_f32_16x16x32_bf16 v[74:77], v[174:177], v[236:239], v[74:77]
	v_mfma_f32_16x16x32_bf16 v[118:121], v[186:189], v[202:205], v[118:121]
	v_mfma_f32_16x16x32_bf16 v[114:117], v[194:197], v[202:205], v[114:117]
	v_mfma_f32_16x16x32_bf16 v[102:105], v[186:189], v[210:213], v[102:105]
	v_mfma_f32_16x16x32_bf16 v[98:101], v[194:197], v[210:213], v[98:101]
	v_mfma_f32_16x16x32_bf16 v[86:89], v[186:189], v[218:221], v[86:89]
	v_mfma_f32_16x16x32_bf16 v[82:85], v[194:197], v[218:221], v[82:85]
	v_mfma_f32_16x16x32_bf16 v[70:73], v[186:189], v[236:239], v[70:73]
	v_mfma_f32_16x16x32_bf16 v[66:69], v[194:197], v[236:239], v[66:69]
	v_mfma_f32_16x16x32_bf16 v[126:129], v[170:173], v[206:209], v[126:129]
	v_mfma_f32_16x16x32_bf16 v[122:125], v[182:185], v[206:209], v[122:125]
	v_mfma_f32_16x16x32_bf16 v[110:113], v[170:173], v[214:217], v[110:113]
	v_mfma_f32_16x16x32_bf16 v[106:109], v[182:185], v[214:217], v[106:109]
	v_mfma_f32_16x16x32_bf16 v[94:97], v[170:173], v[232:235], v[94:97]
	v_mfma_f32_16x16x32_bf16 v[90:93], v[182:185], v[232:235], v[90:93]
	v_mfma_f32_16x16x32_bf16 v[78:81], v[170:173], v[240:243], v[78:81]
	v_mfma_f32_16x16x32_bf16 v[74:77], v[182:185], v[240:243], v[74:77]
	v_mfma_f32_16x16x32_bf16 v[118:121], v[190:193], v[206:209], v[118:121]
	v_mfma_f32_16x16x32_bf16 v[114:117], v[198:201], v[206:209], v[114:117]
	v_mfma_f32_16x16x32_bf16 v[102:105], v[190:193], v[214:217], v[102:105]
	v_mfma_f32_16x16x32_bf16 v[98:101], v[198:201], v[214:217], v[98:101]
	v_mfma_f32_16x16x32_bf16 v[86:89], v[190:193], v[232:235], v[86:89]
	v_mfma_f32_16x16x32_bf16 v[82:85], v[198:201], v[232:235], v[82:85]
	v_mfma_f32_16x16x32_bf16 v[70:73], v[190:193], v[240:243], v[70:73]
	v_mfma_f32_16x16x32_bf16 v[66:69], v[198:201], v[240:243], v[66:69]
	s_setprio 0
	s_barrier
	s_add_i32 s42, s42, s51
	v_lshl_add_u64 v[178:179], s[34:35], 0, v[132:133]
	s_mov_b32 m0, s42
	ds_read_b128 v[202:205], v149 offset:16384
	ds_read_b128 v[206:209], v149 offset:17408
	ds_read_b128 v[210:213], v149 offset:18432
	ds_read_b128 v[214:217], v149 offset:19456
	ds_read_b128 v[218:221], v149 offset:20480
	ds_read_b128 v[232:235], v149 offset:21504
	ds_read_b128 v[236:239], v149 offset:22528
	ds_read_b128 v[240:243], v149 offset:23552
	global_load_lds_dwordx4 v[178:179], off
	s_add_i32 m0, s42, 0x2000
	s_add_u32 s42, s34, 0x40000
	v_lshl_add_u64 v[244:245], s[34:35], 0, v[136:137]
	s_addc_u32 s43, s35, 0
	s_add_i32 s44, s44, s51
	global_load_lds_dwordx4 v[244:245], off
	v_lshl_add_u64 v[246:247], s[42:43], 0, v[132:133]
	s_mov_b32 m0, s44
	v_lshl_add_u64 v[248:249], s[36:37], 0, v[134:135]
	global_load_lds_dwordx4 v[246:247], off
	v_lshl_add_u64 v[246:247], s[42:43], 0, v[136:137]
	s_add_i32 m0, s44, 0x2000
	s_nop 0
	global_load_lds_dwordx4 v[246:247], off
	v_lshl_add_u64 v[246:247], s[36:37], 0, v[130:131]
	s_mov_b32 m0, s19
	s_nop 0
	global_load_lds_dwordx4 v[246:247], off
	s_mov_b32 m0, s56
	s_nop 0
	global_load_lds_dwordx4 v[248:249], off
	s_waitcnt vmcnt(8)
	s_waitcnt lgkmcnt(0)
	s_barrier
; #define PG8_STAGE(bufoff, gbase, voff) do { _Pragma("unroll") for (int _i = 0; _i < 2; ++_i) \
;         __builtin_amdgcn_global_load_lds((const unsigned*)((const char*)(gbase) + (voff)[_i]), (LAS unsigned*)(lds + (bufoff) + ldsw + _i * 8192), 16, 0, 0); } while (0)
; #define PG8_LDA(dst, b, h) do { _Pragma("unroll") for (int m = 0; m < 4; ++m) _Pragma("unroll") for (int k = 0; k < 2; ++k) dst[m][k] = *(const LAS bf16x8*)(lds + PG8_SA(b, h) + aoff + m * 2048 + k * 1024); } while (0)
; #define PG8_LDB(dst, b, h) do { _Pragma("unroll") for (int n = 0; n < 2; ++n) _Pragma("unroll") for (int k = 0; k < 2; ++k) dst[n][k] = *(const LAS bf16x8*)(lds + PG8_SB(b, h) + boff + n * 2048 + k * 1024); } while (0)
; #define PG8_MMA(ai, bj, At, Bt) do { __builtin_amdgcn_s_setprio(1); _Pragma("unroll") for (int m = 0; m < 4; ++m) _Pragma("unroll") for (int n = 0; n < 2; ++n) _Pragma("unroll") for (int k = 0; k < 2; ++k) \
;         acc[ai][bj][m][n] = __builtin_amdgcn_mfma_f32_16x16x32_bf16(Bt[n][k], At[m][k], acc[ai][bj][m][n], 0, 0, 0); __builtin_amdgcn_s_setprio(0); } while (0)
; #define PG8_WAIT_V(n) asm volatile("s_waitcnt vmcnt(" #n ")" ::: "memory")
; #define PG8_WAIT_L(n) asm volatile("s_waitcnt lgkmcnt(" #n ")" ::: "memory")
; #define PG8_BAR __builtin_amdgcn_s_barrier()
; #define PG8_SCHED __builtin_amdgcn_sched_barrier(0)
; template <class Epi>
; __device__ __forceinline__ void gemm_phase(LAS unsigned char* lds, const Gemm g, const StaticOrder& S, const Epi& E) {
;     ...
;             PG8_WAIT_V(8); PG8_WAIT_L(0); PG8_BAR; PG8_MMA(1, 0, At, B0); PG8_MMA(1, 1, At, B1); PG8_BAR; PG8_SCHED;
;             PG8_LDB(B0, 1, 0); PG8_LDB(B1, 1, 1); PG8_SCHED; PG8_LDA(At, 1, 0); PG8_STAGE(PG8_SA(0, 1), a2 + hA, voffA);
;             PG8_WAIT_V(8); PG8_WAIT_L(0); PG8_BAR; PG8_MMA(0, 0, At, B0); PG8_MMA(0, 1, At, B1); PG8_BAR; PG8_SCHED;
	s_setprio 1
	v_mfma_f32_16x16x32_bf16 v[62:65], v[166:169], v[202:205], v[62:65]
	v_mfma_f32_16x16x32_bf16 v[58:61], v[174:177], v[202:205], v[58:61]
	v_mfma_f32_16x16x32_bf16 v[46:49], v[166:169], v[210:213], v[46:49]
	v_mfma_f32_16x16x32_bf16 v[42:45], v[174:177], v[210:213], v[42:45]
	v_mfma_f32_16x16x32_bf16 v[30:33], v[166:169], v[218:221], v[30:33]
	v_mfma_f32_16x16x32_bf16 v[26:29], v[174:177], v[218:221], v[26:29]
	v_mfma_f32_16x16x32_bf16 v[14:17], v[166:169], v[236:239], v[14:17]
	v_mfma_f32_16x16x32_bf16 v[10:13], v[174:177], v[236:239], v[10:13]
	v_mfma_f32_16x16x32_bf16 v[54:57], v[186:189], v[202:205], v[54:57]
	v_mfma_f32_16x16x32_bf16 v[50:53], v[194:197], v[202:205], v[50:53]
	v_mfma_f32_16x16x32_bf16 v[38:41], v[186:189], v[210:213], v[38:41]
	v_mfma_f32_16x16x32_bf16 v[34:37], v[194:197], v[210:213], v[34:37]
	v_mfma_f32_16x16x32_bf16 v[22:25], v[186:189], v[218:221], v[22:25]
	v_mfma_f32_16x16x32_bf16 v[18:21], v[194:197], v[218:221], v[18:21]
	v_mfma_f32_16x16x32_bf16 v[6:9], v[186:189], v[236:239], v[6:9]
	v_mfma_f32_16x16x32_bf16 v[2:5], v[194:197], v[236:239], v[2:5]
	v_mfma_f32_16x16x32_bf16 v[62:65], v[170:173], v[206:209], v[62:65]
	v_mfma_f32_16x16x32_bf16 v[58:61], v[182:185], v[206:209], v[58:61]
	v_mfma_f32_16x16x32_bf16 v[46:49], v[170:173], v[214:217], v[46:49]
	v_mfma_f32_16x16x32_bf16 v[42:45], v[182:185], v[214:217], v[42:45]
	v_mfma_f32_16x16x32_bf16 v[30:33], v[170:173], v[232:235], v[30:33]
	v_mfma_f32_16x16x32_bf16 v[26:29], v[182:185], v[232:235], v[26:29]
	v_mfma_f32_16x16x32_bf16 v[14:17], v[170:173], v[240:243], v[14:17]
	v_mfma_f32_16x16x32_bf16 v[10:13], v[182:185], v[240:243], v[10:13]
	v_mfma_f32_16x16x32_bf16 v[54:57], v[190:193], v[206:209], v[54:57]
	v_mfma_f32_16x16x32_bf16 v[50:53], v[198:201], v[206:209], v[50:53]
	v_mfma_f32_16x16x32_bf16 v[38:41], v[190:193], v[214:217], v[38:41]
	v_mfma_f32_16x16x32_bf16 v[34:37], v[198:201], v[214:217], v[34:37]
	v_mfma_f32_16x16x32_bf16 v[22:25], v[190:193], v[232:235], v[22:25]
	v_mfma_f32_16x16x32_bf16 v[18:21], v[198:201], v[232:235], v[18:21]
	v_mfma_f32_16x16x32_bf16 v[6:9], v[190:193], v[240:243], v[6:9]
	v_mfma_f32_16x16x32_bf16 v[2:5], v[198:201], v[240:243], v[2:5]
	s_setprio 0
	s_barrier
	s_add_i32 s42, 0, 0x18000
	v_add_u32_e32 v153, s42, v139
	s_add_i32 s43, 0, 0x1c000
	ds_read_b128 v[166:169], v153
	ds_read_b128 v[170:173], v153 offset:1024
	ds_read_b128 v[174:177], v153 offset:2048
	ds_read_b128 v[182:185], v153 offset:3072
	v_add_u32_e32 v153, s43, v139
	ds_read_b128 v[186:189], v153
	ds_read_b128 v[190:193], v153 offset:1024
	ds_read_b128 v[194:197], v153 offset:2048
	ds_read_b128 v[198:201], v153 offset:3072
	s_add_u32 s36, s36, 0x40000
	s_addc_u32 s37, s37, 0
	s_mov_b32 m0, s57
	v_lshl_add_u64 v[250:251], s[36:37], 0, v[130:131]
	ds_read_b128 v[202:205], v149 offset:32768
	ds_read_b128 v[206:209], v149 offset:33792
	ds_read_b128 v[210:213], v149 offset:34816
	ds_read_b128 v[214:217], v149 offset:35840
	ds_read_b128 v[218:221], v149 offset:36864
	ds_read_b128 v[232:235], v149 offset:37888
	ds_read_b128 v[236:239], v149 offset:38912
	ds_read_b128 v[240:243], v149 offset:39936
	global_load_lds_dwordx4 v[250:251], off
	v_lshl_add_u64 v[250:251], s[36:37], 0, v[134:135]
	s_mov_b32 m0, s58
	s_nop 0
	global_load_lds_dwordx4 v[250:251], off
	s_waitcnt vmcnt(8)
	s_waitcnt lgkmcnt(0)
	s_barrier
	s_setprio 1
	v_mfma_f32_16x16x32_bf16 v[126:129], v[166:169], v[202:205], v[126:129]
	v_mfma_f32_16x16x32_bf16 v[122:125], v[174:177], v[202:205], v[122:125]
	v_mfma_f32_16x16x32_bf16 v[110:113], v[166:169], v[210:213], v[110:113]
	v_mfma_f32_16x16x32_bf16 v[106:109], v[174:177], v[210:213], v[106:109]
	v_mfma_f32_16x16x32_bf16 v[94:97], v[166:169], v[218:221], v[94:97]
	v_mfma_f32_16x16x32_bf16 v[90:93], v[174:177], v[218:221], v[90:93]
	v_mfma_f32_16x16x32_bf16 v[78:81], v[166:169], v[236:239], v[78:81]
	v_mfma_f32_16x16x32_bf16 v[74:77], v[174:177], v[236:239], v[74:77]
	v_mfma_f32_16x16x32_bf16 v[118:121], v[186:189], v[202:205], v[118:121]
	v_mfma_f32_16x16x32_bf16 v[114:117], v[194:197], v[202:205], v[114:117]
	v_mfma_f32_16x16x32_bf16 v[102:105], v[186:189], v[210:213], v[102:105]
	v_mfma_f32_16x16x32_bf16 v[98:101], v[194:197], v[210:213], v[98:101]
	v_mfma_f32_16x16x32_bf16 v[86:89], v[186:189], v[218:221], v[86:89]
	v_mfma_f32_16x16x32_bf16 v[82:85], v[194:197], v[218:221], v[82:85]
	v_mfma_f32_16x16x32_bf16 v[70:73], v[186:189], v[236:239], v[70:73]
	v_mfma_f32_16x16x32_bf16 v[66:69], v[194:197], v[236:239], v[66:69]
	v_mfma_f32_16x16x32_bf16 v[126:129], v[170:173], v[206:209], v[126:129]
	v_mfma_f32_16x16x32_bf16 v[122:125], v[182:185], v[206:209], v[122:125]
	v_mfma_f32_16x16x32_bf16 v[110:113], v[170:173], v[214:217], v[110:113]
	v_mfma_f32_16x16x32_bf16 v[106:109], v[182:185], v[214:217], v[106:109]
	v_mfma_f32_16x16x32_bf16 v[94:97], v[170:173], v[232:235], v[94:97]
	v_mfma_f32_16x16x32_bf16 v[90:93], v[182:185], v[232:235], v[90:93]
	v_mfma_f32_16x16x32_bf16 v[78:81], v[170:173], v[240:243], v[78:81]
	v_mfma_f32_16x16x32_bf16 v[74:77], v[182:185], v[240:243], v[74:77]
	v_mfma_f32_16x16x32_bf16 v[118:121], v[190:193], v[206:209], v[118:121]
	v_mfma_f32_16x16x32_bf16 v[114:117], v[198:201], v[206:209], v[114:117]
	v_mfma_f32_16x16x32_bf16 v[102:105], v[190:193], v[214:217], v[102:105]
	v_mfma_f32_16x16x32_bf16 v[98:101], v[198:201], v[214:217], v[98:101]
	v_mfma_f32_16x16x32_bf16 v[86:89], v[190:193], v[232:235], v[86:89]
	v_mfma_f32_16x16x32_bf16 v[82:85], v[198:201], v[232:235], v[82:85]
	v_mfma_f32_16x16x32_bf16 v[70:73], v[190:193], v[240:243], v[70:73]
	v_mfma_f32_16x16x32_bf16 v[66:69], v[198:201], v[240:243], v[66:69]
	s_setprio 0
	s_barrier
; #define PG8_STAGE(bufoff, gbase, voff) do { _Pragma("unroll") for (int _i = 0; _i < 2; ++_i) \
;         __builtin_amdgcn_global_load_lds((const unsigned*)((const char*)(gbase) + (voff)[_i]), (LAS unsigned*)(lds + (bufoff) + ldsw + _i * 8192), 16, 0, 0); } while (0)
; #define PG8_LDA(dst, b, h) do { _Pragma("unroll") for (int m = 0; m < 4; ++m) _Pragma("unroll") for (int k = 0; k < 2; ++k) dst[m][k] = *(const LAS bf16x8*)(lds + PG8_SA(b, h) + aoff + m * 2048 + k * 1024); } while (0)
; #define PG8_MMA(ai, bj, At, Bt) do { __builtin_amdgcn_s_setprio(1); _Pragma("unroll") for (int m = 0; m < 4; ++m) _Pragma("unroll") for (int n = 0; n < 2; ++n) _Pragma("unroll") for (int k = 0; k < 2; ++k) \
;         acc[ai][bj][m][n] = __builtin_amdgcn_mfma_f32_16x16x32_bf16(Bt[n][k], At[m][k], acc[ai][bj][m][n], 0, 0, 0); __builtin_amdgcn_s_setprio(0); } while (0)
; #define PG8_WAIT_V(n) asm volatile("s_waitcnt vmcnt(" #n ")" ::: "memory")
; #define PG8_WAIT_L(n) asm volatile("s_waitcnt lgkmcnt(" #n ")" ::: "memory")
; #define PG8_BAR __builtin_amdgcn_s_barrier()
; #define PG8_SCHED __builtin_amdgcn_sched_barrier(0)
; template <class Epi>
; __device__ __forceinline__ void gemm_phase(LAS unsigned char* lds, const Gemm g, const StaticOrder& S, const Epi& E) {
;     ...
;             PG8_LDA(At, 1, 1); PG8_STAGE(PG8_SB(1, 0), b3, voffB); PG8_STAGE(PG8_SB(1, 1), b3 + hB, voffB); PG8_STAGE(PG8_SA(1, 0), a3, voffA);
;             PG8_WAIT_V(8); PG8_WAIT_L(0); PG8_BAR; PG8_MMA(1, 0, At, B0); PG8_MMA(1, 1, At, B1); PG8_BAR; PG8_SCHED;
;         }
	s_add_i32 s36, s42, s51
	v_lshl_add_u64 v[178:179], v[178:179], 0, s[88:89]
	s_mov_b32 m0, s36
	ds_read_b128 v[202:205], v149 offset:49152
	ds_read_b128 v[206:209], v149 offset:50176
	ds_read_b128 v[210:213], v149 offset:51200
	ds_read_b128 v[214:217], v149 offset:52224
	ds_read_b128 v[218:221], v149 offset:53248
	ds_read_b128 v[232:235], v149 offset:54272
	ds_read_b128 v[236:239], v149 offset:55296
	ds_read_b128 v[240:243], v149 offset:56320
	global_load_lds_dwordx4 v[178:179], off
	s_add_i32 m0, s36, 0x2000
	s_add_u32 s34, s34, 0x40080
	v_lshl_add_u64 v[178:179], v[244:245], 0, s[88:89]
	s_addc_u32 s35, s35, 0
	s_add_i32 s36, s43, s51
	global_load_lds_dwordx4 v[178:179], off
	v_lshl_add_u64 v[178:179], s[34:35], 0, v[132:133]
	s_mov_b32 m0, s36
	s_nop 0
	global_load_lds_dwordx4 v[178:179], off
	v_lshl_add_u64 v[178:179], s[34:35], 0, v[136:137]
	s_add_i32 m0, s36, 0x2000
	s_nop 0
	global_load_lds_dwordx4 v[178:179], off
	v_lshl_add_u64 v[178:179], v[246:247], 0, s[88:89]
	s_mov_b32 m0, s60
	s_nop 0
	global_load_lds_dwordx4 v[178:179], off
	v_lshl_add_u64 v[178:179], v[248:249], 0, s[88:89]
	s_mov_b32 m0, s61
	s_nop 0
	global_load_lds_dwordx4 v[178:179], off
	s_waitcnt vmcnt(8)
	s_waitcnt lgkmcnt(0)
	s_barrier
	s_setprio 1
	v_mfma_f32_16x16x32_bf16 v[62:65], v[166:169], v[202:205], v[62:65]
	v_mfma_f32_16x16x32_bf16 v[58:61], v[174:177], v[202:205], v[58:61]
	v_mfma_f32_16x16x32_bf16 v[46:49], v[166:169], v[210:213], v[46:49]
	v_mfma_f32_16x16x32_bf16 v[42:45], v[174:177], v[210:213], v[42:45]
	v_mfma_f32_16x16x32_bf16 v[30:33], v[166:169], v[218:221], v[30:33]
	v_mfma_f32_16x16x32_bf16 v[26:29], v[174:177], v[218:221], v[26:29]
	v_mfma_f32_16x16x32_bf16 v[14:17], v[166:169], v[236:239], v[14:17]
	v_mfma_f32_16x16x32_bf16 v[10:13], v[174:177], v[236:239], v[10:13]
	v_mfma_f32_16x16x32_bf16 v[54:57], v[186:189], v[202:205], v[54:57]
	v_mfma_f32_16x16x32_bf16 v[50:53], v[194:197], v[202:205], v[50:53]
	v_mfma_f32_16x16x32_bf16 v[38:41], v[186:189], v[210:213], v[38:41]
	v_mfma_f32_16x16x32_bf16 v[34:37], v[194:197], v[210:213], v[34:37]
	v_mfma_f32_16x16x32_bf16 v[22:25], v[186:189], v[218:221], v[22:25]
	v_mfma_f32_16x16x32_bf16 v[18:21], v[194:197], v[218:221], v[18:21]
	v_mfma_f32_16x16x32_bf16 v[6:9], v[186:189], v[236:239], v[6:9]
	v_mfma_f32_16x16x32_bf16 v[2:5], v[194:197], v[236:239], v[2:5]
	v_mfma_f32_16x16x32_bf16 v[62:65], v[170:173], v[206:209], v[62:65]
	v_mfma_f32_16x16x32_bf16 v[58:61], v[182:185], v[206:209], v[58:61]
	v_mfma_f32_16x16x32_bf16 v[46:49], v[170:173], v[214:217], v[46:49]
	v_mfma_f32_16x16x32_bf16 v[42:45], v[182:185], v[214:217], v[42:45]
	v_mfma_f32_16x16x32_bf16 v[30:33], v[170:173], v[232:235], v[30:33]
	v_mfma_f32_16x16x32_bf16 v[26:29], v[182:185], v[232:235], v[26:29]
	v_mfma_f32_16x16x32_bf16 v[14:17], v[170:173], v[240:243], v[14:17]
	v_mfma_f32_16x16x32_bf16 v[10:13], v[182:185], v[240:243], v[10:13]
	v_mfma_f32_16x16x32_bf16 v[54:57], v[190:193], v[206:209], v[54:57]
	v_mfma_f32_16x16x32_bf16 v[50:53], v[198:201], v[206:209], v[50:53]
	v_mfma_f32_16x16x32_bf16 v[38:41], v[190:193], v[214:217], v[38:41]
	v_mfma_f32_16x16x32_bf16 v[34:37], v[198:201], v[214:217], v[34:37]
	v_mfma_f32_16x16x32_bf16 v[22:25], v[190:193], v[232:235], v[22:25]
	v_mfma_f32_16x16x32_bf16 v[18:21], v[198:201], v[232:235], v[18:21]
	v_mfma_f32_16x16x32_bf16 v[6:9], v[190:193], v[240:243], v[6:9]
	v_mfma_f32_16x16x32_bf16 v[2:5], v[198:201], v[240:243], v[2:5]
	s_setprio 0
	s_barrier
	s_add_i32 s41, s41, 2
	s_add_u32 s8, s8, 0x100
	s_addc_u32 s9, s9, 0
	s_add_u32 s39, s39, 0x100
	s_addc_u32 s40, s40, 0
	s_cmp_gt_u32 s41, 13
	s_cbranch_scc0 .LBB0_132
	s_and_b64 vcc, exec, s[16:17]
	s_cbranch_vccz .LBB0_135
	s_barrier

; #define PG8_STAGE(bufoff, gbase, voff) do { _Pragma("unroll") for (int _i = 0; _i < 2; ++_i) \
;         __builtin_amdgcn_global_load_lds((const unsigned*)((const char*)(gbase) + (voff)[_i]), (LAS unsigned*)(lds + (bufoff) + ldsw + _i * 8192), 16, 0, 0); } while (0)
; #define PG8_LDA(dst, b, h) do { _Pragma("unroll") for (int m = 0; m < 4; ++m) _Pragma("unroll") for (int k = 0; k < 2; ++k) dst[m][k] = *(const LAS bf16x8*)(lds + PG8_SA(b, h) + aoff + m * 2048 + k * 1024); } while (0)
; #define PG8_LDB(dst, b, h) do { _Pragma("unroll") for (int n = 0; n < 2; ++n) _Pragma("unroll") for (int k = 0; k < 2; ++k) dst[n][k] = *(const LAS bf16x8*)(lds + PG8_SB(b, h) + boff + n * 2048 + k * 1024); } while (0)
; #define PG8_MMA(ai, bj, At, Bt) do { __builtin_amdgcn_s_setprio(1); _Pragma("unroll") for (int m = 0; m < 4; ++m) _Pragma("unroll") for (int n = 0; n < 2; ++n) _Pragma("unroll") for (int k = 0; k < 2; ++k) \
;         acc[ai][bj][m][n] = __builtin_amdgcn_mfma_f32_16x16x32_bf16(Bt[n][k], At[m][k], acc[ai][bj][m][n], 0, 0, 0); __builtin_amdgcn_s_setprio(0); } while (0)
; #define PG8_WAIT_V(n) asm volatile("s_waitcnt vmcnt(" #n ")" ::: "memory")
; #define PG8_WAIT_L(n) asm volatile("s_waitcnt lgkmcnt(" #n ")" ::: "memory")
; #define PG8_BAR __builtin_amdgcn_s_barrier()
; #define PG8_SCHED __builtin_amdgcn_sched_barrier(0)
; template <class Epi>
; __device__ __forceinline__ void gemm_phase(LAS unsigned char* lds, const Gemm g, const StaticOrder& S, const Epi& E) {
;     ...
;         for (int t = 0; t < nt; t += 2) {
;             const bool last = (t == nt - 2);
;             const char* a1 = cA + (size_t)(t + 1) * kstep;
;             const char* a2 = last ? nA : cA + (size_t)(t + 2) * kstep; const char* b2 = last ? nB : cB + (size_t)(t + 2) * kstep;
;             const char* a3 = a2 + kstep; const char* b3 = b2 + kstep;
;             PG8_LDB(B0, 0, 0); PG8_LDB(B1, 0, 1); PG8_SCHED; PG8_LDA(At, 0, 0); PG8_STAGE(PG8_SA(1, 1), a1 + hA, voffA);
;             PG8_WAIT_V(8); PG8_WAIT_L(0); PG8_BAR; PG8_MMA(0, 0, At, B0); PG8_MMA(0, 1, At, B1); PG8_BAR; PG8_SCHED;
;             PG8_LDA(At, 0, 1); PG8_STAGE(PG8_SB(0, 0), b2, voffB); PG8_STAGE(PG8_SB(0, 1), b2 + hB, voffB); PG8_STAGE(PG8_SA(0, 0), a2, voffA);
;             PG8_WAIT_V(8); PG8_WAIT_L(0); PG8_BAR; PG8_MMA(1, 0, At, B0); PG8_MMA(1, 1, At, B1); PG8_BAR; PG8_SCHED;
.LBB0_518:
	s_add_u32 s30, s28, 0xfffc0080
	s_addc_u32 s31, s29, -1
	s_add_i32 s71, 0, 0x10000
	s_cmp_eq_u32 s70, 28
	s_cselect_b32 s35, s21, s31
	s_cselect_b32 s34, s27, s30
	v_add_u32_e32 v154, s71, v156
	s_cselect_b32 s31, s19, s67
	s_cselect_b32 s30, s65, s66
	s_add_i32 s73, 0, 0x14000
	ds_read_b128 v[98:101], v154
	ds_read_b128 v[102:105], v154 offset:1024
	ds_read_b128 v[158:161], v154 offset:2048
	ds_read_b128 v[162:165], v154 offset:3072
	v_add_u32_e32 v154, s73, v156
	ds_read_b128 v[166:169], v154
	ds_read_b128 v[170:173], v154 offset:1024
	ds_read_b128 v[174:177], v154 offset:2048
	ds_read_b128 v[182:185], v154 offset:3072
	v_lshl_add_u64 v[154:155], s[28:29], 0, v[150:151]
	s_add_i32 m0, s54, 0xc000
	ds_read_b128 v[186:189], v157
	ds_read_b128 v[190:193], v157 offset:1024
	ds_read_b128 v[194:197], v157 offset:2048
	ds_read_b128 v[198:201], v157 offset:3072
	ds_read_b128 v[202:205], v157 offset:4096
	ds_read_b128 v[206:209], v157 offset:5120
	ds_read_b128 v[210:213], v157 offset:6144
	ds_read_b128 v[214:217], v157 offset:7168
	global_load_lds_dwordx4 v[154:155], off
	v_lshl_add_u64 v[154:155], s[28:29], 0, v[152:153]
	s_add_i32 m0, s54, 0xe000
	s_nop 0
	global_load_lds_dwordx4 v[154:155], off
	s_waitcnt vmcnt(8)
	s_waitcnt lgkmcnt(0)
	s_barrier
	s_setprio 1
	v_mfma_f32_16x16x32_bf16 v[134:137], v[98:101], v[186:189], v[134:137]
	v_mfma_f32_16x16x32_bf16 v[130:133], v[158:161], v[186:189], v[130:133]
	v_mfma_f32_16x16x32_bf16 v[126:129], v[98:101], v[194:197], v[126:129]
	v_mfma_f32_16x16x32_bf16 v[122:125], v[158:161], v[194:197], v[122:125]
	v_mfma_f32_16x16x32_bf16 v[118:121], v[98:101], v[202:205], v[118:121]
	v_mfma_f32_16x16x32_bf16 v[114:117], v[158:161], v[202:205], v[114:117]
	v_mfma_f32_16x16x32_bf16 v[110:113], v[98:101], v[210:213], v[110:113]
	v_mfma_f32_16x16x32_bf16 v[106:109], v[158:161], v[210:213], v[106:109]
	v_mfma_f32_16x16x32_bf16 v[62:65], v[166:169], v[186:189], v[62:65]
	v_mfma_f32_16x16x32_bf16 v[58:61], v[174:177], v[186:189], v[58:61]
	v_mfma_f32_16x16x32_bf16 v[54:57], v[166:169], v[194:197], v[54:57]
	v_mfma_f32_16x16x32_bf16 v[50:53], v[174:177], v[194:197], v[50:53]
	v_mfma_f32_16x16x32_bf16 v[46:49], v[166:169], v[202:205], v[46:49]
	v_mfma_f32_16x16x32_bf16 v[42:45], v[174:177], v[202:205], v[42:45]
	v_mfma_f32_16x16x32_bf16 v[38:41], v[166:169], v[210:213], v[38:41]
	v_mfma_f32_16x16x32_bf16 v[34:37], v[174:177], v[210:213], v[34:37]
	v_mfma_f32_16x16x32_bf16 v[134:137], v[102:105], v[190:193], v[134:137]
	v_mfma_f32_16x16x32_bf16 v[130:133], v[162:165], v[190:193], v[130:133]
	v_mfma_f32_16x16x32_bf16 v[126:129], v[102:105], v[198:201], v[126:129]
	v_mfma_f32_16x16x32_bf16 v[122:125], v[162:165], v[198:201], v[122:125]
	v_mfma_f32_16x16x32_bf16 v[118:121], v[102:105], v[206:209], v[118:121]
	v_mfma_f32_16x16x32_bf16 v[114:117], v[162:165], v[206:209], v[114:117]
	v_mfma_f32_16x16x32_bf16 v[110:113], v[102:105], v[214:217], v[110:113]
	v_mfma_f32_16x16x32_bf16 v[106:109], v[162:165], v[214:217], v[106:109]
	v_mfma_f32_16x16x32_bf16 v[62:65], v[170:173], v[190:193], v[62:65]
	v_mfma_f32_16x16x32_bf16 v[58:61], v[182:185], v[190:193], v[58:61]
	v_mfma_f32_16x16x32_bf16 v[54:57], v[170:173], v[198:201], v[54:57]
	v_mfma_f32_16x16x32_bf16 v[50:53], v[182:185], v[198:201], v[50:53]
	v_mfma_f32_16x16x32_bf16 v[46:49], v[170:173], v[206:209], v[46:49]
	v_mfma_f32_16x16x32_bf16 v[42:45], v[182:185], v[206:209], v[42:45]
	v_mfma_f32_16x16x32_bf16 v[38:41], v[170:173], v[214:217], v[38:41]
	v_mfma_f32_16x16x32_bf16 v[34:37], v[182:185], v[214:217], v[34:37]
	s_setprio 0
	s_barrier
	s_add_i32 s71, s71, s53
	v_lshl_add_u64 v[154:155], s[30:31], 0, v[140:141]
	s_mov_b32 m0, s71
	ds_read_b128 v[186:189], v157 offset:16384
	ds_read_b128 v[190:193], v157 offset:17408
	ds_read_b128 v[194:197], v157 offset:18432
	ds_read_b128 v[198:201], v157 offset:19456
	ds_read_b128 v[202:205], v157 offset:20480
	ds_read_b128 v[206:209], v157 offset:21504
	ds_read_b128 v[210:213], v157 offset:22528
	ds_read_b128 v[214:217], v157 offset:23552
	global_load_lds_dwordx4 v[154:155], off
	s_add_i32 m0, s71, 0x2000
	s_add_u32 s74, s30, 0x80000
	v_lshl_add_u64 v[178:179], s[30:31], 0, v[144:145]
	s_addc_u32 s75, s31, 0
	s_add_i32 s71, s73, s53
	global_load_lds_dwordx4 v[178:179], off
	v_lshl_add_u64 v[218:219], s[74:75], 0, v[140:141]
	s_mov_b32 m0, s71
	v_lshl_add_u64 v[220:221], s[34:35], 0, v[142:143]
	global_load_lds_dwordx4 v[218:219], off
	v_lshl_add_u64 v[218:219], s[74:75], 0, v[144:145]
	s_add_i32 m0, s71, 0x2000
	s_nop 0
	global_load_lds_dwordx4 v[218:219], off
	v_lshl_add_u64 v[218:219], s[34:35], 0, v[138:139]
	s_mov_b32 m0, s54
	s_nop 0
	global_load_lds_dwordx4 v[218:219], off
	s_mov_b32 m0, s55
	s_nop 0
	global_load_lds_dwordx4 v[220:221], off
	s_waitcnt vmcnt(8)
	s_waitcnt lgkmcnt(0)
	s_barrier
; #define PG8_STAGE(bufoff, gbase, voff) do { _Pragma("unroll") for (int _i = 0; _i < 2; ++_i) \
;         __builtin_amdgcn_global_load_lds((const unsigned*)((const char*)(gbase) + (voff)[_i]), (LAS unsigned*)(lds + (bufoff) + ldsw + _i * 8192), 16, 0, 0); } while (0)
; #define PG8_LDA(dst, b, h) do { _Pragma("unroll") for (int m = 0; m < 4; ++m) _Pragma("unroll") for (int k = 0; k < 2; ++k) dst[m][k] = *(const LAS bf16x8*)(lds + PG8_SA(b, h) + aoff + m * 2048 + k * 1024); } while (0)
; #define PG8_LDB(dst, b, h) do { _Pragma("unroll") for (int n = 0; n < 2; ++n) _Pragma("unroll") for (int k = 0; k < 2; ++k) dst[n][k] = *(const LAS bf16x8*)(lds + PG8_SB(b, h) + boff + n * 2048 + k * 1024); } while (0)
; #define PG8_MMA(ai, bj, At, Bt) do { __builtin_amdgcn_s_setprio(1); _Pragma("unroll") for (int m = 0; m < 4; ++m) _Pragma("unroll") for (int n = 0; n < 2; ++n) _Pragma("unroll") for (int k = 0; k < 2; ++k) \
;         acc[ai][bj][m][n] = __builtin_amdgcn_mfma_f32_16x16x32_bf16(Bt[n][k], At[m][k], acc[ai][bj][m][n], 0, 0, 0); __builtin_amdgcn_s_setprio(0); } while (0)
; #define PG8_WAIT_V(n) asm volatile("s_waitcnt vmcnt(" #n ")" ::: "memory")
; #define PG8_WAIT_L(n) asm volatile("s_waitcnt lgkmcnt(" #n ")" ::: "memory")
; #define PG8_BAR __builtin_amdgcn_s_barrier()
; #define PG8_SCHED __builtin_amdgcn_sched_barrier(0)
; template <class Epi>
; __device__ __forceinline__ void gemm_phase(LAS unsigned char* lds, const Gemm g, const StaticOrder& S, const Epi& E) {
;     ...
;             PG8_WAIT_V(8); PG8_WAIT_L(0); PG8_BAR; PG8_MMA(1, 0, At, B0); PG8_MMA(1, 1, At, B1); PG8_BAR; PG8_SCHED;
;             PG8_LDB(B0, 1, 0); PG8_LDB(B1, 1, 1); PG8_SCHED; PG8_LDA(At, 1, 0); PG8_STAGE(PG8_SA(0, 1), a2 + hA, voffA);
;             PG8_WAIT_V(8); PG8_WAIT_L(0); PG8_BAR; PG8_MMA(0, 0, At, B0); PG8_MMA(0, 1, At, B1); PG8_BAR; PG8_SCHED;
	s_setprio 1
	v_mfma_f32_16x16x32_bf16 v[94:97], v[98:101], v[186:189], v[94:97]
	v_mfma_f32_16x16x32_bf16 v[90:93], v[158:161], v[186:189], v[90:93]
	v_mfma_f32_16x16x32_bf16 v[86:89], v[98:101], v[194:197], v[86:89]
	v_mfma_f32_16x16x32_bf16 v[82:85], v[158:161], v[194:197], v[82:85]
	v_mfma_f32_16x16x32_bf16 v[78:81], v[98:101], v[202:205], v[78:81]
	v_mfma_f32_16x16x32_bf16 v[74:77], v[158:161], v[202:205], v[74:77]
	v_mfma_f32_16x16x32_bf16 v[70:73], v[98:101], v[210:213], v[70:73]
	v_mfma_f32_16x16x32_bf16 v[66:69], v[158:161], v[210:213], v[66:69]
	v_mfma_f32_16x16x32_bf16 v[30:33], v[166:169], v[186:189], v[30:33]
	v_mfma_f32_16x16x32_bf16 v[26:29], v[174:177], v[186:189], v[26:29]
	v_mfma_f32_16x16x32_bf16 v[22:25], v[166:169], v[194:197], v[22:25]
	v_mfma_f32_16x16x32_bf16 v[18:21], v[174:177], v[194:197], v[18:21]
	v_mfma_f32_16x16x32_bf16 v[14:17], v[166:169], v[202:205], v[14:17]
	v_mfma_f32_16x16x32_bf16 v[10:13], v[174:177], v[202:205], v[10:13]
	v_mfma_f32_16x16x32_bf16 v[6:9], v[166:169], v[210:213], v[6:9]
	v_mfma_f32_16x16x32_bf16 v[2:5], v[174:177], v[210:213], v[2:5]
	v_mfma_f32_16x16x32_bf16 v[94:97], v[102:105], v[190:193], v[94:97]
	v_mfma_f32_16x16x32_bf16 v[90:93], v[162:165], v[190:193], v[90:93]
	v_mfma_f32_16x16x32_bf16 v[86:89], v[102:105], v[198:201], v[86:89]
	v_mfma_f32_16x16x32_bf16 v[82:85], v[162:165], v[198:201], v[82:85]
	v_mfma_f32_16x16x32_bf16 v[78:81], v[102:105], v[206:209], v[78:81]
	v_mfma_f32_16x16x32_bf16 v[74:77], v[162:165], v[206:209], v[74:77]
	v_mfma_f32_16x16x32_bf16 v[70:73], v[102:105], v[214:217], v[70:73]
	v_mfma_f32_16x16x32_bf16 v[66:69], v[162:165], v[214:217], v[66:69]
	v_mfma_f32_16x16x32_bf16 v[30:33], v[170:173], v[190:193], v[30:33]
	v_mfma_f32_16x16x32_bf16 v[26:29], v[182:185], v[190:193], v[26:29]
	v_mfma_f32_16x16x32_bf16 v[22:25], v[170:173], v[198:201], v[22:25]
	v_mfma_f32_16x16x32_bf16 v[18:21], v[182:185], v[198:201], v[18:21]
	v_mfma_f32_16x16x32_bf16 v[14:17], v[170:173], v[206:209], v[14:17]
	v_mfma_f32_16x16x32_bf16 v[10:13], v[182:185], v[206:209], v[10:13]
	v_mfma_f32_16x16x32_bf16 v[6:9], v[170:173], v[214:217], v[6:9]
	v_mfma_f32_16x16x32_bf16 v[2:5], v[182:185], v[214:217], v[2:5]
	s_setprio 0
	s_barrier
	s_add_i32 s71, 0, 0x18000
	s_add_i32 s73, 0, 0x1c000
	v_add_u32_e32 v162, s71, v156
	v_add_u32_e32 v180, s73, v156
	ds_read_b128 v[98:101], v162
	ds_read_b128 v[102:105], v162 offset:1024
	ds_read_b128 v[158:161], v162 offset:2048
	ds_read_b128 v[162:165], v162 offset:3072
	ds_read_b128 v[166:169], v180
	ds_read_b128 v[170:173], v180 offset:1024
	ds_read_b128 v[174:177], v180 offset:2048
	ds_read_b128 v[182:185], v180 offset:3072
	s_add_u32 s34, s34, 0x40000
	s_addc_u32 s35, s35, 0
	s_mov_b32 m0, s56
	v_lshl_add_u64 v[232:233], s[34:35], 0, v[138:139]
	ds_read_b128 v[186:189], v157 offset:32768
	ds_read_b128 v[190:193], v157 offset:33792
	ds_read_b128 v[194:197], v157 offset:34816
	ds_read_b128 v[198:201], v157 offset:35840
	ds_read_b128 v[202:205], v157 offset:36864
	ds_read_b128 v[206:209], v157 offset:37888
	ds_read_b128 v[210:213], v157 offset:38912
	ds_read_b128 v[214:217], v157 offset:39936
	global_load_lds_dwordx4 v[232:233], off
	v_lshl_add_u64 v[232:233], s[34:35], 0, v[142:143]
	s_mov_b32 m0, s57
	s_nop 0
	global_load_lds_dwordx4 v[232:233], off
	s_waitcnt vmcnt(8)
	s_waitcnt lgkmcnt(0)
	s_barrier
	s_setprio 1
	v_mfma_f32_16x16x32_bf16 v[134:137], v[98:101], v[186:189], v[134:137]
	v_mfma_f32_16x16x32_bf16 v[130:133], v[158:161], v[186:189], v[130:133]
	v_mfma_f32_16x16x32_bf16 v[126:129], v[98:101], v[194:197], v[126:129]
	v_mfma_f32_16x16x32_bf16 v[122:125], v[158:161], v[194:197], v[122:125]
	v_mfma_f32_16x16x32_bf16 v[118:121], v[98:101], v[202:205], v[118:121]
	v_mfma_f32_16x16x32_bf16 v[114:117], v[158:161], v[202:205], v[114:117]
	v_mfma_f32_16x16x32_bf16 v[110:113], v[98:101], v[210:213], v[110:113]
	v_mfma_f32_16x16x32_bf16 v[106:109], v[158:161], v[210:213], v[106:109]
	v_mfma_f32_16x16x32_bf16 v[62:65], v[166:169], v[186:189], v[62:65]
	v_mfma_f32_16x16x32_bf16 v[58:61], v[174:177], v[186:189], v[58:61]
	v_mfma_f32_16x16x32_bf16 v[54:57], v[166:169], v[194:197], v[54:57]
	v_mfma_f32_16x16x32_bf16 v[50:53], v[174:177], v[194:197], v[50:53]
	v_mfma_f32_16x16x32_bf16 v[46:49], v[166:169], v[202:205], v[46:49]
	v_mfma_f32_16x16x32_bf16 v[42:45], v[174:177], v[202:205], v[42:45]
	v_mfma_f32_16x16x32_bf16 v[38:41], v[166:169], v[210:213], v[38:41]
	v_mfma_f32_16x16x32_bf16 v[34:37], v[174:177], v[210:213], v[34:37]
	v_mfma_f32_16x16x32_bf16 v[134:137], v[102:105], v[190:193], v[134:137]
	v_mfma_f32_16x16x32_bf16 v[130:133], v[162:165], v[190:193], v[130:133]
	v_mfma_f32_16x16x32_bf16 v[126:129], v[102:105], v[198:201], v[126:129]
	v_mfma_f32_16x16x32_bf16 v[122:125], v[162:165], v[198:201], v[122:125]
	v_mfma_f32_16x16x32_bf16 v[118:121], v[102:105], v[206:209], v[118:121]
	v_mfma_f32_16x16x32_bf16 v[114:117], v[162:165], v[206:209], v[114:117]
	v_mfma_f32_16x16x32_bf16 v[110:113], v[102:105], v[214:217], v[110:113]
	v_mfma_f32_16x16x32_bf16 v[106:109], v[162:165], v[214:217], v[106:109]
	v_mfma_f32_16x16x32_bf16 v[62:65], v[170:173], v[190:193], v[62:65]
	v_mfma_f32_16x16x32_bf16 v[58:61], v[182:185], v[190:193], v[58:61]
	v_mfma_f32_16x16x32_bf16 v[54:57], v[170:173], v[198:201], v[54:57]
	v_mfma_f32_16x16x32_bf16 v[50:53], v[182:185], v[198:201], v[50:53]
	v_mfma_f32_16x16x32_bf16 v[46:49], v[170:173], v[206:209], v[46:49]
	v_mfma_f32_16x16x32_bf16 v[42:45], v[182:185], v[206:209], v[42:45]
	v_mfma_f32_16x16x32_bf16 v[38:41], v[170:173], v[214:217], v[38:41]
	v_mfma_f32_16x16x32_bf16 v[34:37], v[182:185], v[214:217], v[34:37]
	s_setprio 0
	s_barrier
; #define PG8_STAGE(bufoff, gbase, voff) do { _Pragma("unroll") for (int _i = 0; _i < 2; ++_i) \
;         __builtin_amdgcn_global_load_lds((const unsigned*)((const char*)(gbase) + (voff)[_i]), (LAS unsigned*)(lds + (bufoff) + ldsw + _i * 8192), 16, 0, 0); } while (0)
; #define PG8_LDA(dst, b, h) do { _Pragma("unroll") for (int m = 0; m < 4; ++m) _Pragma("unroll") for (int k = 0; k < 2; ++k) dst[m][k] = *(const LAS bf16x8*)(lds + PG8_SA(b, h) + aoff + m * 2048 + k * 1024); } while (0)
; #define PG8_MMA(ai, bj, At, Bt) do { __builtin_amdgcn_s_setprio(1); _Pragma("unroll") for (int m = 0; m < 4; ++m) _Pragma("unroll") for (int n = 0; n < 2; ++n) _Pragma("unroll") for (int k = 0; k < 2; ++k) \
;         acc[ai][bj][m][n] = __builtin_amdgcn_mfma_f32_16x16x32_bf16(Bt[n][k], At[m][k], acc[ai][bj][m][n], 0, 0, 0); __builtin_amdgcn_s_setprio(0); } while (0)
; #define PG8_WAIT_V(n) asm volatile("s_waitcnt vmcnt(" #n ")" ::: "memory")
; #define PG8_WAIT_L(n) asm volatile("s_waitcnt lgkmcnt(" #n ")" ::: "memory")
; #define PG8_BAR __builtin_amdgcn_s_barrier()
; #define PG8_SCHED __builtin_amdgcn_sched_barrier(0)
; template <class Epi>
; __device__ __forceinline__ void gemm_phase(LAS unsigned char* lds, const Gemm g, const StaticOrder& S, const Epi& E) {
;     ...
;             PG8_LDA(At, 1, 1); PG8_STAGE(PG8_SB(1, 0), b3, voffB); PG8_STAGE(PG8_SB(1, 1), b3 + hB, voffB); PG8_STAGE(PG8_SA(1, 0), a3, voffA);
;             PG8_WAIT_V(8); PG8_WAIT_L(0); PG8_BAR; PG8_MMA(1, 0, At, B0); PG8_MMA(1, 1, At, B1); PG8_BAR; PG8_SCHED;
;         }
	s_add_i32 s34, s71, s53
	v_lshl_add_u64 v[154:155], v[154:155], 0, s[88:89]
	s_mov_b32 m0, s34
	ds_read_b128 v[186:189], v157 offset:49152
	ds_read_b128 v[190:193], v157 offset:50176
	ds_read_b128 v[194:197], v157 offset:51200
	ds_read_b128 v[198:201], v157 offset:52224
	ds_read_b128 v[202:205], v157 offset:53248
	ds_read_b128 v[206:209], v157 offset:54272
	ds_read_b128 v[210:213], v157 offset:55296
	ds_read_b128 v[214:217], v157 offset:56320
	global_load_lds_dwordx4 v[154:155], off
	s_add_i32 m0, s34, 0x2000
	s_add_u32 s30, s30, 0x80080
	v_lshl_add_u64 v[154:155], v[178:179], 0, s[88:89]
	s_addc_u32 s31, s31, 0
	s_add_i32 s34, s73, s53
	global_load_lds_dwordx4 v[154:155], off
	v_lshl_add_u64 v[154:155], s[30:31], 0, v[140:141]
	s_mov_b32 m0, s34
	s_nop 0
	global_load_lds_dwordx4 v[154:155], off
	v_lshl_add_u64 v[154:155], s[30:31], 0, v[144:145]
	s_add_i32 m0, s34, 0x2000
	s_nop 0
	global_load_lds_dwordx4 v[154:155], off
	v_lshl_add_u64 v[154:155], v[218:219], 0, s[88:89]
	s_mov_b32 m0, s59
	s_nop 0
	global_load_lds_dwordx4 v[154:155], off
	v_lshl_add_u64 v[154:155], v[220:221], 0, s[88:89]
	s_mov_b32 m0, s60
	s_nop 0
	global_load_lds_dwordx4 v[154:155], off
	s_waitcnt vmcnt(8)
	s_waitcnt lgkmcnt(0)
	s_barrier
	s_setprio 1
	v_mfma_f32_16x16x32_bf16 v[94:97], v[98:101], v[186:189], v[94:97]
	v_mfma_f32_16x16x32_bf16 v[90:93], v[158:161], v[186:189], v[90:93]
	v_mfma_f32_16x16x32_bf16 v[86:89], v[98:101], v[194:197], v[86:89]
	v_mfma_f32_16x16x32_bf16 v[82:85], v[158:161], v[194:197], v[82:85]
	v_mfma_f32_16x16x32_bf16 v[78:81], v[98:101], v[202:205], v[78:81]
	v_mfma_f32_16x16x32_bf16 v[74:77], v[158:161], v[202:205], v[74:77]
	v_mfma_f32_16x16x32_bf16 v[70:73], v[98:101], v[210:213], v[70:73]
	v_mfma_f32_16x16x32_bf16 v[66:69], v[158:161], v[210:213], v[66:69]
	v_mfma_f32_16x16x32_bf16 v[30:33], v[166:169], v[186:189], v[30:33]
	v_mfma_f32_16x16x32_bf16 v[26:29], v[174:177], v[186:189], v[26:29]
	v_mfma_f32_16x16x32_bf16 v[22:25], v[166:169], v[194:197], v[22:25]
	v_mfma_f32_16x16x32_bf16 v[18:21], v[174:177], v[194:197], v[18:21]
	v_mfma_f32_16x16x32_bf16 v[14:17], v[166:169], v[202:205], v[14:17]
	v_mfma_f32_16x16x32_bf16 v[10:13], v[174:177], v[202:205], v[10:13]
	v_mfma_f32_16x16x32_bf16 v[6:9], v[166:169], v[210:213], v[6:9]
	v_mfma_f32_16x16x32_bf16 v[2:5], v[174:177], v[210:213], v[2:5]
	v_mfma_f32_16x16x32_bf16 v[94:97], v[102:105], v[190:193], v[94:97]
	v_mfma_f32_16x16x32_bf16 v[90:93], v[162:165], v[190:193], v[90:93]
	v_mfma_f32_16x16x32_bf16 v[86:89], v[102:105], v[198:201], v[86:89]
	v_mfma_f32_16x16x32_bf16 v[82:85], v[162:165], v[198:201], v[82:85]
	v_mfma_f32_16x16x32_bf16 v[78:81], v[102:105], v[206:209], v[78:81]
	v_mfma_f32_16x16x32_bf16 v[74:77], v[162:165], v[206:209], v[74:77]
	v_mfma_f32_16x16x32_bf16 v[70:73], v[102:105], v[214:217], v[70:73]
	v_mfma_f32_16x16x32_bf16 v[66:69], v[162:165], v[214:217], v[66:69]
	v_mfma_f32_16x16x32_bf16 v[30:33], v[170:173], v[190:193], v[30:33]
	v_mfma_f32_16x16x32_bf16 v[26:29], v[182:185], v[190:193], v[26:29]
	v_mfma_f32_16x16x32_bf16 v[22:25], v[170:173], v[198:201], v[22:25]
	v_mfma_f32_16x16x32_bf16 v[18:21], v[182:185], v[198:201], v[18:21]
	v_mfma_f32_16x16x32_bf16 v[14:17], v[170:173], v[206:209], v[14:17]
	v_mfma_f32_16x16x32_bf16 v[10:13], v[182:185], v[206:209], v[10:13]
	v_mfma_f32_16x16x32_bf16 v[6:9], v[170:173], v[214:217], v[6:9]
	v_mfma_f32_16x16x32_bf16 v[2:5], v[182:185], v[214:217], v[2:5]
	s_setprio 0
	s_barrier
	s_add_i32 s70, s70, 2
	s_add_u32 s28, s28, 0x100
	s_addc_u32 s29, s29, 0
	s_add_u32 s66, s66, 0x100
	s_addc_u32 s67, s67, 0
	s_cmp_gt_u32 s70, 29
	s_cbranch_scc0 .LBB0_518
	s_and_b64 vcc, exec, s[16:17]
	s_cbranch_vccz .LBB0_521
	s_barrier

; #define PG8_STAGE(bufoff, gbase, voff) do { _Pragma("unroll") for (int _i = 0; _i < 2; ++_i) \
;         __builtin_amdgcn_global_load_lds((const unsigned*)((const char*)(gbase) + (voff)[_i]), (LAS unsigned*)(lds + (bufoff) + ldsw + _i * 8192), 16, 0, 0); } while (0)
; #define PG8_LDA(dst, b, h) do { _Pragma("unroll") for (int m = 0; m < 4; ++m) _Pragma("unroll") for (int k = 0; k < 2; ++k) dst[m][k] = *(const LAS bf16x8*)(lds + PG8_SA(b, h) + aoff + m * 2048 + k * 1024); } while (0)
; #define PG8_LDB(dst, b, h) do { _Pragma("unroll") for (int n = 0; n < 2; ++n) _Pragma("unroll") for (int k = 0; k < 2; ++k) dst[n][k] = *(const LAS bf16x8*)(lds + PG8_SB(b, h) + boff + n * 2048 + k * 1024); } while (0)
; #define PG8_MMA(ai, bj, At, Bt) do { __builtin_amdgcn_s_setprio(1); _Pragma("unroll") for (int m = 0; m < 4; ++m) _Pragma("unroll") for (int n = 0; n < 2; ++n) _Pragma("unroll") for (int k = 0; k < 2; ++k) \
;         acc[ai][bj][m][n] = __builtin_amdgcn_mfma_f32_16x16x32_bf16(Bt[n][k], At[m][k], acc[ai][bj][m][n], 0, 0, 0); __builtin_amdgcn_s_setprio(0); } while (0)
; #define PG8_WAIT_V(n) asm volatile("s_waitcnt vmcnt(" #n ")" ::: "memory")
; #define PG8_WAIT_L(n) asm volatile("s_waitcnt lgkmcnt(" #n ")" ::: "memory")
; #define PG8_BAR __builtin_amdgcn_s_barrier()
; #define PG8_SCHED __builtin_amdgcn_sched_barrier(0)
; template <class Epi>
; __device__ __forceinline__ void gemm_phase(LAS unsigned char* lds, const Gemm g, const StaticOrder& S, const Epi& E) {
;     ...
;         for (int t = 0; t < nt; t += 2) {
;             const bool last = (t == nt - 2);
;             const char* a1 = cA + (size_t)(t + 1) * kstep;
;             const char* a2 = last ? nA : cA + (size_t)(t + 2) * kstep; const char* b2 = last ? nB : cB + (size_t)(t + 2) * kstep;
;             const char* a3 = a2 + kstep; const char* b3 = b2 + kstep;
;             PG8_LDB(B0, 0, 0); PG8_LDB(B1, 0, 1); PG8_SCHED; PG8_LDA(At, 0, 0); PG8_STAGE(PG8_SA(1, 1), a1 + hA, voffA);
;             PG8_WAIT_V(8); PG8_WAIT_L(0); PG8_BAR; PG8_MMA(0, 0, At, B0); PG8_MMA(0, 1, At, B1); PG8_BAR; PG8_SCHED;
;             PG8_LDA(At, 0, 1); PG8_STAGE(PG8_SB(0, 0), b2, voffB); PG8_STAGE(PG8_SB(0, 1), b2 + hB, voffB); PG8_STAGE(PG8_SA(0, 0), a2, voffA);
;             PG8_WAIT_V(8); PG8_WAIT_L(0); PG8_BAR; PG8_MMA(1, 0, At, B0); PG8_MMA(1, 1, At, B1); PG8_BAR; PG8_SCHED;
.LBB0_1398:
	s_add_u32 s10, s8, 0xfffc0080
	s_addc_u32 s11, s9, -1
	s_add_i32 s35, 0, 0x10000
	s_cmp_eq_u32 s31, 12
	s_cselect_b32 s41, s37, s11
	s_cselect_b32 s40, s36, s10
	s_cselect_b32 s11, s39, s29
	s_cselect_b32 s10, s38, s27
	s_add_i32 s64, 0, 0x14000
	v_add_u32_e32 v158, s35, v180
	v_add_u32_e32 v174, s64, v180
	ds_read_b128 v[146:149], v158
	ds_read_b128 v[150:153], v158 offset:1024
	ds_read_b128 v[154:157], v158 offset:2048
	ds_read_b128 v[158:161], v158 offset:3072
	ds_read_b128 v[162:165], v174
	ds_read_b128 v[166:169], v174 offset:1024
	ds_read_b128 v[170:173], v174 offset:2048
	ds_read_b128 v[174:177], v174 offset:3072
	v_lshl_add_u64 v[178:179], s[8:9], 0, v[142:143]
	s_add_i32 m0, s51, 0xc000
	ds_read_b128 v[182:185], v211
	ds_read_b128 v[186:189], v211 offset:1024
	ds_read_b128 v[190:193], v211 offset:2048
	ds_read_b128 v[194:197], v211 offset:3072
	ds_read_b128 v[198:201], v211 offset:4096
	ds_read_b128 v[202:205], v211 offset:5120
	ds_read_b128 v[216:219], v211 offset:6144
	ds_read_b128 v[232:235], v211 offset:7168
	global_load_lds_dwordx4 v[178:179], off
	v_lshl_add_u64 v[178:179], s[8:9], 0, v[144:145]
	s_add_i32 m0, s51, 0xe000
	s_nop 0
	global_load_lds_dwordx4 v[178:179], off
	s_waitcnt vmcnt(8)
	s_waitcnt lgkmcnt(0)
	s_barrier
	s_setprio 1
	v_mfma_f32_16x16x32_bf16 v[126:129], v[146:149], v[182:185], v[126:129]
	v_mfma_f32_16x16x32_bf16 v[122:125], v[154:157], v[182:185], v[122:125]
	v_mfma_f32_16x16x32_bf16 v[110:113], v[146:149], v[190:193], v[110:113]
	v_mfma_f32_16x16x32_bf16 v[106:109], v[154:157], v[190:193], v[106:109]
	v_mfma_f32_16x16x32_bf16 v[94:97], v[146:149], v[198:201], v[94:97]
	v_mfma_f32_16x16x32_bf16 v[90:93], v[154:157], v[198:201], v[90:93]
	v_mfma_f32_16x16x32_bf16 v[78:81], v[146:149], v[216:219], v[78:81]
	v_mfma_f32_16x16x32_bf16 v[74:77], v[154:157], v[216:219], v[74:77]
	v_mfma_f32_16x16x32_bf16 v[118:121], v[162:165], v[182:185], v[118:121]
	v_mfma_f32_16x16x32_bf16 v[114:117], v[170:173], v[182:185], v[114:117]
	v_mfma_f32_16x16x32_bf16 v[102:105], v[162:165], v[190:193], v[102:105]
	v_mfma_f32_16x16x32_bf16 v[98:101], v[170:173], v[190:193], v[98:101]
	v_mfma_f32_16x16x32_bf16 v[86:89], v[162:165], v[198:201], v[86:89]
	v_mfma_f32_16x16x32_bf16 v[82:85], v[170:173], v[198:201], v[82:85]
	v_mfma_f32_16x16x32_bf16 v[70:73], v[162:165], v[216:219], v[70:73]
	v_mfma_f32_16x16x32_bf16 v[66:69], v[170:173], v[216:219], v[66:69]
	v_mfma_f32_16x16x32_bf16 v[126:129], v[150:153], v[186:189], v[126:129]
	v_mfma_f32_16x16x32_bf16 v[122:125], v[158:161], v[186:189], v[122:125]
	v_mfma_f32_16x16x32_bf16 v[110:113], v[150:153], v[194:197], v[110:113]
	v_mfma_f32_16x16x32_bf16 v[106:109], v[158:161], v[194:197], v[106:109]
	v_mfma_f32_16x16x32_bf16 v[94:97], v[150:153], v[202:205], v[94:97]
	v_mfma_f32_16x16x32_bf16 v[90:93], v[158:161], v[202:205], v[90:93]
	v_mfma_f32_16x16x32_bf16 v[78:81], v[150:153], v[232:235], v[78:81]
	v_mfma_f32_16x16x32_bf16 v[74:77], v[158:161], v[232:235], v[74:77]
	v_mfma_f32_16x16x32_bf16 v[118:121], v[166:169], v[186:189], v[118:121]
	v_mfma_f32_16x16x32_bf16 v[114:117], v[174:177], v[186:189], v[114:117]
	v_mfma_f32_16x16x32_bf16 v[102:105], v[166:169], v[194:197], v[102:105]
	v_mfma_f32_16x16x32_bf16 v[98:101], v[174:177], v[194:197], v[98:101]
	v_mfma_f32_16x16x32_bf16 v[86:89], v[166:169], v[202:205], v[86:89]
	v_mfma_f32_16x16x32_bf16 v[82:85], v[174:177], v[202:205], v[82:85]
	v_mfma_f32_16x16x32_bf16 v[70:73], v[166:169], v[232:235], v[70:73]
	v_mfma_f32_16x16x32_bf16 v[66:69], v[174:177], v[232:235], v[66:69]
	s_setprio 0
	s_barrier
	s_add_i32 s35, s35, s50
	v_lshl_add_u64 v[178:179], s[10:11], 0, v[132:133]
	s_mov_b32 m0, s35
	ds_read_b128 v[182:185], v211 offset:16384
	ds_read_b128 v[186:189], v211 offset:17408
	ds_read_b128 v[190:193], v211 offset:18432
	ds_read_b128 v[194:197], v211 offset:19456
	ds_read_b128 v[198:201], v211 offset:20480
	ds_read_b128 v[202:205], v211 offset:21504
	ds_read_b128 v[216:219], v211 offset:22528
	ds_read_b128 v[232:235], v211 offset:23552
	global_load_lds_dwordx4 v[178:179], off
	s_add_i32 m0, s35, 0x2000
	s_add_u32 s42, s10, 0x40000
	v_lshl_add_u64 v[206:207], s[10:11], 0, v[136:137]
	s_addc_u32 s43, s11, 0
	s_add_i32 s35, s64, s50
	global_load_lds_dwordx4 v[206:207], off
	v_lshl_add_u64 v[220:221], s[42:43], 0, v[132:133]
	s_mov_b32 m0, s35
	v_lshl_add_u64 v[236:237], s[40:41], 0, v[134:135]
	global_load_lds_dwordx4 v[220:221], off
	v_lshl_add_u64 v[220:221], s[42:43], 0, v[136:137]
	s_add_i32 m0, s35, 0x2000
	s_nop 0
	global_load_lds_dwordx4 v[220:221], off
	v_lshl_add_u64 v[220:221], s[40:41], 0, v[130:131]
	s_mov_b32 m0, s51
	s_nop 0
	global_load_lds_dwordx4 v[220:221], off
	s_mov_b32 m0, s52
	s_nop 0
	global_load_lds_dwordx4 v[236:237], off
	s_waitcnt vmcnt(8)
	s_waitcnt lgkmcnt(0)
	s_barrier
; #define PG8_STAGE(bufoff, gbase, voff) do { _Pragma("unroll") for (int _i = 0; _i < 2; ++_i) \
;         __builtin_amdgcn_global_load_lds((const unsigned*)((const char*)(gbase) + (voff)[_i]), (LAS unsigned*)(lds + (bufoff) + ldsw + _i * 8192), 16, 0, 0); } while (0)
; #define PG8_LDA(dst, b, h) do { _Pragma("unroll") for (int m = 0; m < 4; ++m) _Pragma("unroll") for (int k = 0; k < 2; ++k) dst[m][k] = *(const LAS bf16x8*)(lds + PG8_SA(b, h) + aoff + m * 2048 + k * 1024); } while (0)
; #define PG8_LDB(dst, b, h) do { _Pragma("unroll") for (int n = 0; n < 2; ++n) _Pragma("unroll") for (int k = 0; k < 2; ++k) dst[n][k] = *(const LAS bf16x8*)(lds + PG8_SB(b, h) + boff + n * 2048 + k * 1024); } while (0)
; #define PG8_MMA(ai, bj, At, Bt) do { __builtin_amdgcn_s_setprio(1); _Pragma("unroll") for (int m = 0; m < 4; ++m) _Pragma("unroll") for (int n = 0; n < 2; ++n) _Pragma("unroll") for (int k = 0; k < 2; ++k) \
;         acc[ai][bj][m][n] = __builtin_amdgcn_mfma_f32_16x16x32_bf16(Bt[n][k], At[m][k], acc[ai][bj][m][n], 0, 0, 0); __builtin_amdgcn_s_setprio(0); } while (0)
; #define PG8_WAIT_V(n) asm volatile("s_waitcnt vmcnt(" #n ")" ::: "memory")
; #define PG8_WAIT_L(n) asm volatile("s_waitcnt lgkmcnt(" #n ")" ::: "memory")
; #define PG8_BAR __builtin_amdgcn_s_barrier()
; #define PG8_SCHED __builtin_amdgcn_sched_barrier(0)
; template <class Epi>
; __device__ __forceinline__ void gemm_phase(LAS unsigned char* lds, const Gemm g, const StaticOrder& S, const Epi& E) {
;     ...
;             PG8_WAIT_V(8); PG8_WAIT_L(0); PG8_BAR; PG8_MMA(1, 0, At, B0); PG8_MMA(1, 1, At, B1); PG8_BAR; PG8_SCHED;
;             PG8_LDB(B0, 1, 0); PG8_LDB(B1, 1, 1); PG8_SCHED; PG8_LDA(At, 1, 0); PG8_STAGE(PG8_SA(0, 1), a2 + hA, voffA);
;             PG8_WAIT_V(8); PG8_WAIT_L(0); PG8_BAR; PG8_MMA(0, 0, At, B0); PG8_MMA(0, 1, At, B1); PG8_BAR; PG8_SCHED;
	s_setprio 1
	v_mfma_f32_16x16x32_bf16 v[62:65], v[146:149], v[182:185], v[62:65]
	v_mfma_f32_16x16x32_bf16 v[58:61], v[154:157], v[182:185], v[58:61]
	v_mfma_f32_16x16x32_bf16 v[46:49], v[146:149], v[190:193], v[46:49]
	v_mfma_f32_16x16x32_bf16 v[42:45], v[154:157], v[190:193], v[42:45]
	v_mfma_f32_16x16x32_bf16 v[30:33], v[146:149], v[198:201], v[30:33]
	v_mfma_f32_16x16x32_bf16 v[26:29], v[154:157], v[198:201], v[26:29]
	v_mfma_f32_16x16x32_bf16 v[14:17], v[146:149], v[216:219], v[14:17]
	v_mfma_f32_16x16x32_bf16 v[10:13], v[154:157], v[216:219], v[10:13]
	v_mfma_f32_16x16x32_bf16 v[54:57], v[162:165], v[182:185], v[54:57]
	v_mfma_f32_16x16x32_bf16 v[50:53], v[170:173], v[182:185], v[50:53]
	v_mfma_f32_16x16x32_bf16 v[38:41], v[162:165], v[190:193], v[38:41]
	v_mfma_f32_16x16x32_bf16 v[34:37], v[170:173], v[190:193], v[34:37]
	v_mfma_f32_16x16x32_bf16 v[22:25], v[162:165], v[198:201], v[22:25]
	v_mfma_f32_16x16x32_bf16 v[18:21], v[170:173], v[198:201], v[18:21]
	v_mfma_f32_16x16x32_bf16 v[6:9], v[162:165], v[216:219], v[6:9]
	v_mfma_f32_16x16x32_bf16 v[2:5], v[170:173], v[216:219], v[2:5]
	v_mfma_f32_16x16x32_bf16 v[62:65], v[150:153], v[186:189], v[62:65]
	v_mfma_f32_16x16x32_bf16 v[58:61], v[158:161], v[186:189], v[58:61]
	v_mfma_f32_16x16x32_bf16 v[46:49], v[150:153], v[194:197], v[46:49]
	v_mfma_f32_16x16x32_bf16 v[42:45], v[158:161], v[194:197], v[42:45]
	v_mfma_f32_16x16x32_bf16 v[30:33], v[150:153], v[202:205], v[30:33]
	v_mfma_f32_16x16x32_bf16 v[26:29], v[158:161], v[202:205], v[26:29]
	v_mfma_f32_16x16x32_bf16 v[14:17], v[150:153], v[232:235], v[14:17]
	v_mfma_f32_16x16x32_bf16 v[10:13], v[158:161], v[232:235], v[10:13]
	v_mfma_f32_16x16x32_bf16 v[54:57], v[166:169], v[186:189], v[54:57]
	v_mfma_f32_16x16x32_bf16 v[50:53], v[174:177], v[186:189], v[50:53]
	v_mfma_f32_16x16x32_bf16 v[38:41], v[166:169], v[194:197], v[38:41]
	v_mfma_f32_16x16x32_bf16 v[34:37], v[174:177], v[194:197], v[34:37]
	v_mfma_f32_16x16x32_bf16 v[22:25], v[166:169], v[202:205], v[22:25]
	v_mfma_f32_16x16x32_bf16 v[18:21], v[174:177], v[202:205], v[18:21]
	v_mfma_f32_16x16x32_bf16 v[6:9], v[166:169], v[232:235], v[6:9]
	v_mfma_f32_16x16x32_bf16 v[2:5], v[174:177], v[232:235], v[2:5]
	s_setprio 0
	s_barrier
	s_add_i32 s35, 0, 0x18000
	s_add_i32 s42, 0, 0x1c000
	v_add_u32_e32 v158, s35, v180
	v_add_u32_e32 v174, s42, v180
	ds_read_b128 v[146:149], v158
	ds_read_b128 v[150:153], v158 offset:1024
	ds_read_b128 v[154:157], v158 offset:2048
	ds_read_b128 v[158:161], v158 offset:3072
	ds_read_b128 v[162:165], v174
	ds_read_b128 v[166:169], v174 offset:1024
	ds_read_b128 v[170:173], v174 offset:2048
	ds_read_b128 v[174:177], v174 offset:3072
	s_add_u32 s40, s40, 0x40000
	s_addc_u32 s41, s41, 0
	s_mov_b32 m0, s53
	v_lshl_add_u64 v[238:239], s[40:41], 0, v[130:131]
	ds_read_b128 v[182:185], v211 offset:32768
	ds_read_b128 v[186:189], v211 offset:33792
	ds_read_b128 v[190:193], v211 offset:34816
	ds_read_b128 v[194:197], v211 offset:35840
	ds_read_b128 v[198:201], v211 offset:36864
	ds_read_b128 v[202:205], v211 offset:37888
	ds_read_b128 v[216:219], v211 offset:38912
	ds_read_b128 v[232:235], v211 offset:39936
	global_load_lds_dwordx4 v[238:239], off
	v_lshl_add_u64 v[238:239], s[40:41], 0, v[134:135]
	s_mov_b32 m0, s54
	s_nop 0
	global_load_lds_dwordx4 v[238:239], off
	s_waitcnt vmcnt(8)
	s_waitcnt lgkmcnt(0)
	s_barrier
	s_setprio 1
	v_mfma_f32_16x16x32_bf16 v[126:129], v[146:149], v[182:185], v[126:129]
	v_mfma_f32_16x16x32_bf16 v[122:125], v[154:157], v[182:185], v[122:125]
	v_mfma_f32_16x16x32_bf16 v[110:113], v[146:149], v[190:193], v[110:113]
	v_mfma_f32_16x16x32_bf16 v[106:109], v[154:157], v[190:193], v[106:109]
	v_mfma_f32_16x16x32_bf16 v[94:97], v[146:149], v[198:201], v[94:97]
	v_mfma_f32_16x16x32_bf16 v[90:93], v[154:157], v[198:201], v[90:93]
	v_mfma_f32_16x16x32_bf16 v[78:81], v[146:149], v[216:219], v[78:81]
	v_mfma_f32_16x16x32_bf16 v[74:77], v[154:157], v[216:219], v[74:77]
	v_mfma_f32_16x16x32_bf16 v[118:121], v[162:165], v[182:185], v[118:121]
	v_mfma_f32_16x16x32_bf16 v[114:117], v[170:173], v[182:185], v[114:117]
	v_mfma_f32_16x16x32_bf16 v[102:105], v[162:165], v[190:193], v[102:105]
	v_mfma_f32_16x16x32_bf16 v[98:101], v[170:173], v[190:193], v[98:101]
	v_mfma_f32_16x16x32_bf16 v[86:89], v[162:165], v[198:201], v[86:89]
	v_mfma_f32_16x16x32_bf16 v[82:85], v[170:173], v[198:201], v[82:85]
	v_mfma_f32_16x16x32_bf16 v[70:73], v[162:165], v[216:219], v[70:73]
	v_mfma_f32_16x16x32_bf16 v[66:69], v[170:173], v[216:219], v[66:69]
	v_mfma_f32_16x16x32_bf16 v[126:129], v[150:153], v[186:189], v[126:129]
	v_mfma_f32_16x16x32_bf16 v[122:125], v[158:161], v[186:189], v[122:125]
	v_mfma_f32_16x16x32_bf16 v[110:113], v[150:153], v[194:197], v[110:113]
	v_mfma_f32_16x16x32_bf16 v[106:109], v[158:161], v[194:197], v[106:109]
	v_mfma_f32_16x16x32_bf16 v[94:97], v[150:153], v[202:205], v[94:97]
	v_mfma_f32_16x16x32_bf16 v[90:93], v[158:161], v[202:205], v[90:93]
	v_mfma_f32_16x16x32_bf16 v[78:81], v[150:153], v[232:235], v[78:81]
	v_mfma_f32_16x16x32_bf16 v[74:77], v[158:161], v[232:235], v[74:77]
	v_mfma_f32_16x16x32_bf16 v[118:121], v[166:169], v[186:189], v[118:121]
	v_mfma_f32_16x16x32_bf16 v[114:117], v[174:177], v[186:189], v[114:117]
	v_mfma_f32_16x16x32_bf16 v[102:105], v[166:169], v[194:197], v[102:105]
	v_mfma_f32_16x16x32_bf16 v[98:101], v[174:177], v[194:197], v[98:101]
	v_mfma_f32_16x16x32_bf16 v[86:89], v[166:169], v[202:205], v[86:89]
	v_mfma_f32_16x16x32_bf16 v[82:85], v[174:177], v[202:205], v[82:85]
	v_mfma_f32_16x16x32_bf16 v[70:73], v[166:169], v[232:235], v[70:73]
	v_mfma_f32_16x16x32_bf16 v[66:69], v[174:177], v[232:235], v[66:69]
	s_setprio 0
	s_barrier
; #define PG8_STAGE(bufoff, gbase, voff) do { _Pragma("unroll") for (int _i = 0; _i < 2; ++_i) \
;         __builtin_amdgcn_global_load_lds((const unsigned*)((const char*)(gbase) + (voff)[_i]), (LAS unsigned*)(lds + (bufoff) + ldsw + _i * 8192), 16, 0, 0); } while (0)
; #define PG8_LDA(dst, b, h) do { _Pragma("unroll") for (int m = 0; m < 4; ++m) _Pragma("unroll") for (int k = 0; k < 2; ++k) dst[m][k] = *(const LAS bf16x8*)(lds + PG8_SA(b, h) + aoff + m * 2048 + k * 1024); } while (0)
; #define PG8_MMA(ai, bj, At, Bt) do { __builtin_amdgcn_s_setprio(1); _Pragma("unroll") for (int m = 0; m < 4; ++m) _Pragma("unroll") for (int n = 0; n < 2; ++n) _Pragma("unroll") for (int k = 0; k < 2; ++k) \
;         acc[ai][bj][m][n] = __builtin_amdgcn_mfma_f32_16x16x32_bf16(Bt[n][k], At[m][k], acc[ai][bj][m][n], 0, 0, 0); __builtin_amdgcn_s_setprio(0); } while (0)
; #define PG8_WAIT_V(n) asm volatile("s_waitcnt vmcnt(" #n ")" ::: "memory")
; #define PG8_WAIT_L(n) asm volatile("s_waitcnt lgkmcnt(" #n ")" ::: "memory")
; #define PG8_BAR __builtin_amdgcn_s_barrier()
; #define PG8_SCHED __builtin_amdgcn_sched_barrier(0)
; template <class Epi>
; __device__ __forceinline__ void gemm_phase(LAS unsigned char* lds, const Gemm g, const StaticOrder& S, const Epi& E) {
;     ...
;             PG8_LDA(At, 1, 1); PG8_STAGE(PG8_SB(1, 0), b3, voffB); PG8_STAGE(PG8_SB(1, 1), b3 + hB, voffB); PG8_STAGE(PG8_SA(1, 0), a3, voffA);
;             PG8_WAIT_V(8); PG8_WAIT_L(0); PG8_BAR; PG8_MMA(1, 0, At, B0); PG8_MMA(1, 1, At, B1); PG8_BAR; PG8_SCHED;
;         }
	s_add_i32 s35, s35, s50
	v_lshl_add_u64 v[178:179], v[178:179], 0, s[88:89]
	s_mov_b32 m0, s35
	ds_read_b128 v[182:185], v211 offset:49152
	ds_read_b128 v[186:189], v211 offset:50176
	ds_read_b128 v[190:193], v211 offset:51200
	ds_read_b128 v[194:197], v211 offset:52224
	ds_read_b128 v[198:201], v211 offset:53248
	ds_read_b128 v[202:205], v211 offset:54272
	ds_read_b128 v[216:219], v211 offset:55296
	ds_read_b128 v[232:235], v211 offset:56320
	global_load_lds_dwordx4 v[178:179], off
	s_add_i32 m0, s35, 0x2000
	s_add_u32 s10, s10, 0x40080
	v_lshl_add_u64 v[178:179], v[206:207], 0, s[88:89]
	s_addc_u32 s11, s11, 0
	s_add_i32 s35, s42, s50
	global_load_lds_dwordx4 v[178:179], off
	v_lshl_add_u64 v[178:179], s[10:11], 0, v[132:133]
	s_mov_b32 m0, s35
	s_nop 0
	global_load_lds_dwordx4 v[178:179], off
	v_lshl_add_u64 v[178:179], s[10:11], 0, v[136:137]
	s_add_i32 m0, s35, 0x2000
	s_nop 0
	global_load_lds_dwordx4 v[178:179], off
	v_lshl_add_u64 v[178:179], v[220:221], 0, s[88:89]
	s_mov_b32 m0, s55
	s_nop 0
	global_load_lds_dwordx4 v[178:179], off
	v_lshl_add_u64 v[178:179], v[236:237], 0, s[88:89]
	s_mov_b32 m0, s56
	s_nop 0
	global_load_lds_dwordx4 v[178:179], off
	s_waitcnt vmcnt(8)
	s_waitcnt lgkmcnt(0)
	s_barrier
	s_setprio 1
	v_mfma_f32_16x16x32_bf16 v[62:65], v[146:149], v[182:185], v[62:65]
	v_mfma_f32_16x16x32_bf16 v[58:61], v[154:157], v[182:185], v[58:61]
	v_mfma_f32_16x16x32_bf16 v[46:49], v[146:149], v[190:193], v[46:49]
	v_mfma_f32_16x16x32_bf16 v[42:45], v[154:157], v[190:193], v[42:45]
	v_mfma_f32_16x16x32_bf16 v[30:33], v[146:149], v[198:201], v[30:33]
	v_mfma_f32_16x16x32_bf16 v[26:29], v[154:157], v[198:201], v[26:29]
	v_mfma_f32_16x16x32_bf16 v[14:17], v[146:149], v[216:219], v[14:17]
	v_mfma_f32_16x16x32_bf16 v[10:13], v[154:157], v[216:219], v[10:13]
	v_mfma_f32_16x16x32_bf16 v[54:57], v[162:165], v[182:185], v[54:57]
	v_mfma_f32_16x16x32_bf16 v[50:53], v[170:173], v[182:185], v[50:53]
	v_mfma_f32_16x16x32_bf16 v[38:41], v[162:165], v[190:193], v[38:41]
	v_mfma_f32_16x16x32_bf16 v[34:37], v[170:173], v[190:193], v[34:37]
	v_mfma_f32_16x16x32_bf16 v[22:25], v[162:165], v[198:201], v[22:25]
	v_mfma_f32_16x16x32_bf16 v[18:21], v[170:173], v[198:201], v[18:21]
	v_mfma_f32_16x16x32_bf16 v[6:9], v[162:165], v[216:219], v[6:9]
	v_mfma_f32_16x16x32_bf16 v[2:5], v[170:173], v[216:219], v[2:5]
	v_mfma_f32_16x16x32_bf16 v[62:65], v[150:153], v[186:189], v[62:65]
	v_mfma_f32_16x16x32_bf16 v[58:61], v[158:161], v[186:189], v[58:61]
	v_mfma_f32_16x16x32_bf16 v[46:49], v[150:153], v[194:197], v[46:49]
	v_mfma_f32_16x16x32_bf16 v[42:45], v[158:161], v[194:197], v[42:45]
	v_mfma_f32_16x16x32_bf16 v[30:33], v[150:153], v[202:205], v[30:33]
	v_mfma_f32_16x16x32_bf16 v[26:29], v[158:161], v[202:205], v[26:29]
	v_mfma_f32_16x16x32_bf16 v[14:17], v[150:153], v[232:235], v[14:17]
	v_mfma_f32_16x16x32_bf16 v[10:13], v[158:161], v[232:235], v[10:13]
	v_mfma_f32_16x16x32_bf16 v[54:57], v[166:169], v[186:189], v[54:57]
	v_mfma_f32_16x16x32_bf16 v[50:53], v[174:177], v[186:189], v[50:53]
	v_mfma_f32_16x16x32_bf16 v[38:41], v[166:169], v[194:197], v[38:41]
	v_mfma_f32_16x16x32_bf16 v[34:37], v[174:177], v[194:197], v[34:37]
	v_mfma_f32_16x16x32_bf16 v[22:25], v[166:169], v[202:205], v[22:25]
	v_mfma_f32_16x16x32_bf16 v[18:21], v[174:177], v[202:205], v[18:21]
	v_mfma_f32_16x16x32_bf16 v[6:9], v[166:169], v[232:235], v[6:9]
	v_mfma_f32_16x16x32_bf16 v[2:5], v[174:177], v[232:235], v[2:5]
	s_setprio 0
	s_barrier
	s_add_i32 s31, s31, 2
	s_add_u32 s8, s8, 0x100
	s_addc_u32 s9, s9, 0
	s_add_u32 s27, s27, 0x100
	s_addc_u32 s29, s29, 0
	s_cmp_gt_u32 s31, 13
	s_cbranch_scc0 .LBB0_1398
	s_and_b64 vcc, exec, s[16:17]
	s_cbranch_vccz .LBB0_1401
	s_barrier

; #define PG8_STAGE(bufoff, gbase, voff) do { _Pragma("unroll") for (int _i = 0; _i < 2; ++_i) \
;         __builtin_amdgcn_global_load_lds((const unsigned*)((const char*)(gbase) + (voff)[_i]), (LAS unsigned*)(lds + (bufoff) + ldsw + _i * 8192), 16, 0, 0); } while (0)
; #define PG8_LDA(dst, b, h) do { _Pragma("unroll") for (int m = 0; m < 4; ++m) _Pragma("unroll") for (int k = 0; k < 2; ++k) dst[m][k] = *(const LAS bf16x8*)(lds + PG8_SA(b, h) + aoff + m * 2048 + k * 1024); } while (0)
; #define PG8_LDB(dst, b, h) do { _Pragma("unroll") for (int n = 0; n < 2; ++n) _Pragma("unroll") for (int k = 0; k < 2; ++k) dst[n][k] = *(const LAS bf16x8*)(lds + PG8_SB(b, h) + boff + n * 2048 + k * 1024); } while (0)
; #define PG8_MMA(ai, bj, At, Bt) do { __builtin_amdgcn_s_setprio(1); _Pragma("unroll") for (int m = 0; m < 4; ++m) _Pragma("unroll") for (int n = 0; n < 2; ++n) _Pragma("unroll") for (int k = 0; k < 2; ++k) \
;         acc[ai][bj][m][n] = __builtin_amdgcn_mfma_f32_16x16x32_bf16(Bt[n][k], At[m][k], acc[ai][bj][m][n], 0, 0, 0); __builtin_amdgcn_s_setprio(0); } while (0)
; #define PG8_WAIT_V(n) asm volatile("s_waitcnt vmcnt(" #n ")" ::: "memory")
; #define PG8_WAIT_L(n) asm volatile("s_waitcnt lgkmcnt(" #n ")" ::: "memory")
; #define PG8_BAR __builtin_amdgcn_s_barrier()
; #define PG8_SCHED __builtin_amdgcn_sched_barrier(0)
; template <class Epi>
; __device__ __forceinline__ void gemm_phase(LAS unsigned char* lds, const Gemm g, const StaticOrder& S, const Epi& E) {
;     ...
;         for (int t = 0; t < nt; t += 2) {
;             const bool last = (t == nt - 2);
;             const char* a1 = cA + (size_t)(t + 1) * kstep;
;             const char* a2 = last ? nA : cA + (size_t)(t + 2) * kstep; const char* b2 = last ? nB : cB + (size_t)(t + 2) * kstep;
;             const char* a3 = a2 + kstep; const char* b3 = b2 + kstep;
;             PG8_LDB(B0, 0, 0); PG8_LDB(B1, 0, 1); PG8_SCHED; PG8_LDA(At, 0, 0); PG8_STAGE(PG8_SA(1, 1), a1 + hA, voffA);
;             PG8_WAIT_V(8); PG8_WAIT_L(0); PG8_BAR; PG8_MMA(0, 0, At, B0); PG8_MMA(0, 1, At, B1); PG8_BAR; PG8_SCHED;
;             PG8_LDA(At, 0, 1); PG8_STAGE(PG8_SB(0, 0), b2, voffB); PG8_STAGE(PG8_SB(0, 1), b2 + hB, voffB); PG8_STAGE(PG8_SA(0, 0), a2, voffA);
;             PG8_WAIT_V(8); PG8_WAIT_L(0); PG8_BAR; PG8_MMA(1, 0, At, B0); PG8_MMA(1, 1, At, B1); PG8_BAR; PG8_SCHED;
.LBB0_1550:
	s_add_u32 s22, s20, 0xfffc0080
	s_addc_u32 s23, s21, -1
	s_add_i32 s51, 0, 0x10000
	s_cmp_eq_u32 s50, 12
	s_cselect_b32 s25, s15, s23
	s_cselect_b32 s24, s46, s22
	v_add_u32_e32 v142, s51, v143
	s_cselect_b32 s23, s13, s49
	s_cselect_b32 s22, s47, s48
	s_add_i32 s54, 0, 0x14000
	ds_read_b128 v[148:151], v142
	ds_read_b128 v[152:155], v142 offset:1024
	ds_read_b128 v[156:159], v142 offset:2048
	ds_read_b128 v[160:163], v142 offset:3072
	v_add_u32_e32 v142, s54, v143
	ds_read_b128 v[164:167], v142
	ds_read_b128 v[168:171], v142 offset:1024
	ds_read_b128 v[172:175], v142 offset:2048
	ds_read_b128 v[176:179], v142 offset:3072
	v_lshl_add_u64 v[214:215], s[20:21], 0, v[138:139]
	s_add_i32 m0, s34, 0xc000
	ds_read_b128 v[182:185], v147
	ds_read_b128 v[186:189], v147 offset:1024
	ds_read_b128 v[190:193], v147 offset:2048
	ds_read_b128 v[194:197], v147 offset:3072
	ds_read_b128 v[198:201], v147 offset:4096
	ds_read_b128 v[202:205], v147 offset:5120
	ds_read_b128 v[206:209], v147 offset:6144
	ds_read_b128 v[210:213], v147 offset:7168
	global_load_lds_dwordx4 v[214:215], off
	v_lshl_add_u64 v[214:215], s[20:21], 0, v[140:141]
	s_add_i32 m0, s34, 0xe000
	s_nop 0
	global_load_lds_dwordx4 v[214:215], off
	s_waitcnt vmcnt(8)
	s_waitcnt lgkmcnt(0)
	s_barrier
	s_setprio 1
	v_mfma_f32_16x16x32_bf16 v[126:129], v[148:151], v[182:185], v[126:129]
	v_mfma_f32_16x16x32_bf16 v[122:125], v[156:159], v[182:185], v[122:125]
	v_mfma_f32_16x16x32_bf16 v[110:113], v[148:151], v[190:193], v[110:113]
	v_mfma_f32_16x16x32_bf16 v[106:109], v[156:159], v[190:193], v[106:109]
	v_mfma_f32_16x16x32_bf16 v[94:97], v[148:151], v[198:201], v[94:97]
	v_mfma_f32_16x16x32_bf16 v[90:93], v[156:159], v[198:201], v[90:93]
	v_mfma_f32_16x16x32_bf16 v[78:81], v[148:151], v[206:209], v[78:81]
	v_mfma_f32_16x16x32_bf16 v[74:77], v[156:159], v[206:209], v[74:77]
	v_mfma_f32_16x16x32_bf16 v[118:121], v[164:167], v[182:185], v[118:121]
	v_mfma_f32_16x16x32_bf16 v[114:117], v[172:175], v[182:185], v[114:117]
	v_mfma_f32_16x16x32_bf16 v[102:105], v[164:167], v[190:193], v[102:105]
	v_mfma_f32_16x16x32_bf16 v[98:101], v[172:175], v[190:193], v[98:101]
	v_mfma_f32_16x16x32_bf16 v[86:89], v[164:167], v[198:201], v[86:89]
	v_mfma_f32_16x16x32_bf16 v[82:85], v[172:175], v[198:201], v[82:85]
	v_mfma_f32_16x16x32_bf16 v[70:73], v[164:167], v[206:209], v[70:73]
	v_mfma_f32_16x16x32_bf16 v[66:69], v[172:175], v[206:209], v[66:69]
	v_mfma_f32_16x16x32_bf16 v[126:129], v[152:155], v[186:189], v[126:129]
	v_mfma_f32_16x16x32_bf16 v[122:125], v[160:163], v[186:189], v[122:125]
	v_mfma_f32_16x16x32_bf16 v[110:113], v[152:155], v[194:197], v[110:113]
	v_mfma_f32_16x16x32_bf16 v[106:109], v[160:163], v[194:197], v[106:109]
	v_mfma_f32_16x16x32_bf16 v[94:97], v[152:155], v[202:205], v[94:97]
	v_mfma_f32_16x16x32_bf16 v[90:93], v[160:163], v[202:205], v[90:93]
	v_mfma_f32_16x16x32_bf16 v[78:81], v[152:155], v[210:213], v[78:81]
	v_mfma_f32_16x16x32_bf16 v[74:77], v[160:163], v[210:213], v[74:77]
	v_mfma_f32_16x16x32_bf16 v[118:121], v[168:171], v[186:189], v[118:121]
	v_mfma_f32_16x16x32_bf16 v[114:117], v[176:179], v[186:189], v[114:117]
	v_mfma_f32_16x16x32_bf16 v[102:105], v[168:171], v[194:197], v[102:105]
	v_mfma_f32_16x16x32_bf16 v[98:101], v[176:179], v[194:197], v[98:101]
	v_mfma_f32_16x16x32_bf16 v[86:89], v[168:171], v[202:205], v[86:89]
	v_mfma_f32_16x16x32_bf16 v[82:85], v[176:179], v[202:205], v[82:85]
	v_mfma_f32_16x16x32_bf16 v[70:73], v[168:171], v[210:213], v[70:73]
	v_mfma_f32_16x16x32_bf16 v[66:69], v[176:179], v[210:213], v[66:69]
	s_setprio 0
	s_barrier
	s_add_i32 s51, s51, s31
	v_lshl_add_u64 v[214:215], s[22:23], 0, v[134:135]
	s_mov_b32 m0, s51
	ds_read_b128 v[182:185], v147 offset:16384
	ds_read_b128 v[186:189], v147 offset:17408
	ds_read_b128 v[190:193], v147 offset:18432
	ds_read_b128 v[194:197], v147 offset:19456
	ds_read_b128 v[198:201], v147 offset:20480
	ds_read_b128 v[202:205], v147 offset:21504
	ds_read_b128 v[206:209], v147 offset:22528
	ds_read_b128 v[210:213], v147 offset:23552
	global_load_lds_dwordx4 v[214:215], off
	s_add_i32 m0, s51, 0x2000
	s_add_u32 s52, s22, 0x40000
	v_lshl_add_u64 v[216:217], s[22:23], 0, v[130:131]
	s_addc_u32 s53, s23, 0
	s_add_i32 s51, s54, s31
	global_load_lds_dwordx4 v[216:217], off
	v_lshl_add_u64 v[218:219], s[52:53], 0, v[134:135]
	s_mov_b32 m0, s51
	v_lshl_add_u64 v[220:221], s[24:25], 0, v[132:133]
	global_load_lds_dwordx4 v[218:219], off
	v_lshl_add_u64 v[218:219], s[52:53], 0, v[130:131]
	s_add_i32 m0, s51, 0x2000
	s_nop 0
	global_load_lds_dwordx4 v[218:219], off
	v_lshl_add_u64 v[218:219], s[24:25], 0, v[136:137]
	s_mov_b32 m0, s34
	s_nop 0
	global_load_lds_dwordx4 v[218:219], off
	s_mov_b32 m0, s35
	s_nop 0
	global_load_lds_dwordx4 v[220:221], off
	s_waitcnt vmcnt(8)
	s_waitcnt lgkmcnt(0)
	s_barrier
; #define PG8_STAGE(bufoff, gbase, voff) do { _Pragma("unroll") for (int _i = 0; _i < 2; ++_i) \
;         __builtin_amdgcn_global_load_lds((const unsigned*)((const char*)(gbase) + (voff)[_i]), (LAS unsigned*)(lds + (bufoff) + ldsw + _i * 8192), 16, 0, 0); } while (0)
; #define PG8_LDA(dst, b, h) do { _Pragma("unroll") for (int m = 0; m < 4; ++m) _Pragma("unroll") for (int k = 0; k < 2; ++k) dst[m][k] = *(const LAS bf16x8*)(lds + PG8_SA(b, h) + aoff + m * 2048 + k * 1024); } while (0)
; #define PG8_LDB(dst, b, h) do { _Pragma("unroll") for (int n = 0; n < 2; ++n) _Pragma("unroll") for (int k = 0; k < 2; ++k) dst[n][k] = *(const LAS bf16x8*)(lds + PG8_SB(b, h) + boff + n * 2048 + k * 1024); } while (0)
; #define PG8_MMA(ai, bj, At, Bt) do { __builtin_amdgcn_s_setprio(1); _Pragma("unroll") for (int m = 0; m < 4; ++m) _Pragma("unroll") for (int n = 0; n < 2; ++n) _Pragma("unroll") for (int k = 0; k < 2; ++k) \
;         acc[ai][bj][m][n] = __builtin_amdgcn_mfma_f32_16x16x32_bf16(Bt[n][k], At[m][k], acc[ai][bj][m][n], 0, 0, 0); __builtin_amdgcn_s_setprio(0); } while (0)
; #define PG8_WAIT_V(n) asm volatile("s_waitcnt vmcnt(" #n ")" ::: "memory")
; #define PG8_WAIT_L(n) asm volatile("s_waitcnt lgkmcnt(" #n ")" ::: "memory")
; #define PG8_BAR __builtin_amdgcn_s_barrier()
; #define PG8_SCHED __builtin_amdgcn_sched_barrier(0)
; template <class Epi>
; __device__ __forceinline__ void gemm_phase(LAS unsigned char* lds, const Gemm g, const StaticOrder& S, const Epi& E) {
;     ...
;             PG8_WAIT_V(8); PG8_WAIT_L(0); PG8_BAR; PG8_MMA(1, 0, At, B0); PG8_MMA(1, 1, At, B1); PG8_BAR; PG8_SCHED;
;             PG8_LDB(B0, 1, 0); PG8_LDB(B1, 1, 1); PG8_SCHED; PG8_LDA(At, 1, 0); PG8_STAGE(PG8_SA(0, 1), a2 + hA, voffA);
;             PG8_WAIT_V(8); PG8_WAIT_L(0); PG8_BAR; PG8_MMA(0, 0, At, B0); PG8_MMA(0, 1, At, B1); PG8_BAR; PG8_SCHED;
	s_setprio 1
	v_mfma_f32_16x16x32_bf16 v[62:65], v[148:151], v[182:185], v[62:65]
	v_mfma_f32_16x16x32_bf16 v[58:61], v[156:159], v[182:185], v[58:61]
	v_mfma_f32_16x16x32_bf16 v[46:49], v[148:151], v[190:193], v[46:49]
	v_mfma_f32_16x16x32_bf16 v[42:45], v[156:159], v[190:193], v[42:45]
	v_mfma_f32_16x16x32_bf16 v[30:33], v[148:151], v[198:201], v[30:33]
	v_mfma_f32_16x16x32_bf16 v[26:29], v[156:159], v[198:201], v[26:29]
	v_mfma_f32_16x16x32_bf16 v[14:17], v[148:151], v[206:209], v[14:17]
	v_mfma_f32_16x16x32_bf16 v[10:13], v[156:159], v[206:209], v[10:13]
	v_mfma_f32_16x16x32_bf16 v[54:57], v[164:167], v[182:185], v[54:57]
	v_mfma_f32_16x16x32_bf16 v[50:53], v[172:175], v[182:185], v[50:53]
	v_mfma_f32_16x16x32_bf16 v[38:41], v[164:167], v[190:193], v[38:41]
	v_mfma_f32_16x16x32_bf16 v[34:37], v[172:175], v[190:193], v[34:37]
	v_mfma_f32_16x16x32_bf16 v[22:25], v[164:167], v[198:201], v[22:25]
	v_mfma_f32_16x16x32_bf16 v[18:21], v[172:175], v[198:201], v[18:21]
	v_mfma_f32_16x16x32_bf16 v[6:9], v[164:167], v[206:209], v[6:9]
	v_mfma_f32_16x16x32_bf16 v[2:5], v[172:175], v[206:209], v[2:5]
	v_mfma_f32_16x16x32_bf16 v[62:65], v[152:155], v[186:189], v[62:65]
	v_mfma_f32_16x16x32_bf16 v[58:61], v[160:163], v[186:189], v[58:61]
	v_mfma_f32_16x16x32_bf16 v[46:49], v[152:155], v[194:197], v[46:49]
	v_mfma_f32_16x16x32_bf16 v[42:45], v[160:163], v[194:197], v[42:45]
	v_mfma_f32_16x16x32_bf16 v[30:33], v[152:155], v[202:205], v[30:33]
	v_mfma_f32_16x16x32_bf16 v[26:29], v[160:163], v[202:205], v[26:29]
	v_mfma_f32_16x16x32_bf16 v[14:17], v[152:155], v[210:213], v[14:17]
	v_mfma_f32_16x16x32_bf16 v[10:13], v[160:163], v[210:213], v[10:13]
	v_mfma_f32_16x16x32_bf16 v[54:57], v[168:171], v[186:189], v[54:57]
	v_mfma_f32_16x16x32_bf16 v[50:53], v[176:179], v[186:189], v[50:53]
	v_mfma_f32_16x16x32_bf16 v[38:41], v[168:171], v[194:197], v[38:41]
	v_mfma_f32_16x16x32_bf16 v[34:37], v[176:179], v[194:197], v[34:37]
	v_mfma_f32_16x16x32_bf16 v[22:25], v[168:171], v[202:205], v[22:25]
	v_mfma_f32_16x16x32_bf16 v[18:21], v[176:179], v[202:205], v[18:21]
	v_mfma_f32_16x16x32_bf16 v[6:9], v[168:171], v[210:213], v[6:9]
	v_mfma_f32_16x16x32_bf16 v[2:5], v[176:179], v[210:213], v[2:5]
	s_setprio 0
	s_barrier
	s_add_i32 s51, 0, 0x18000
	v_add_u32_e32 v142, s51, v143
	s_add_i32 s52, 0, 0x1c000
	ds_read_b128 v[148:151], v142
	ds_read_b128 v[152:155], v142 offset:1024
	ds_read_b128 v[156:159], v142 offset:2048
	ds_read_b128 v[160:163], v142 offset:3072
	v_add_u32_e32 v142, s52, v143
	ds_read_b128 v[164:167], v142
	ds_read_b128 v[168:171], v142 offset:1024
	ds_read_b128 v[172:175], v142 offset:2048
	ds_read_b128 v[176:179], v142 offset:3072
	s_add_u32 s24, s24, 0x40000
	s_addc_u32 s25, s25, 0
	s_mov_b32 m0, s36
	v_lshl_add_u64 v[232:233], s[24:25], 0, v[136:137]
	ds_read_b128 v[182:185], v147 offset:32768
	ds_read_b128 v[186:189], v147 offset:33792
	ds_read_b128 v[190:193], v147 offset:34816
	ds_read_b128 v[194:197], v147 offset:35840
	ds_read_b128 v[198:201], v147 offset:36864
	ds_read_b128 v[202:205], v147 offset:37888
	ds_read_b128 v[206:209], v147 offset:38912
	ds_read_b128 v[210:213], v147 offset:39936
	global_load_lds_dwordx4 v[232:233], off
	v_lshl_add_u64 v[232:233], s[24:25], 0, v[132:133]
	s_mov_b32 m0, s37
	s_nop 0
	global_load_lds_dwordx4 v[232:233], off
	s_waitcnt vmcnt(8)
	s_waitcnt lgkmcnt(0)
	s_barrier
	s_setprio 1
	v_mfma_f32_16x16x32_bf16 v[126:129], v[148:151], v[182:185], v[126:129]
	v_mfma_f32_16x16x32_bf16 v[122:125], v[156:159], v[182:185], v[122:125]
	v_mfma_f32_16x16x32_bf16 v[110:113], v[148:151], v[190:193], v[110:113]
	v_mfma_f32_16x16x32_bf16 v[106:109], v[156:159], v[190:193], v[106:109]
	v_mfma_f32_16x16x32_bf16 v[94:97], v[148:151], v[198:201], v[94:97]
	v_mfma_f32_16x16x32_bf16 v[90:93], v[156:159], v[198:201], v[90:93]
	v_mfma_f32_16x16x32_bf16 v[78:81], v[148:151], v[206:209], v[78:81]
	v_mfma_f32_16x16x32_bf16 v[74:77], v[156:159], v[206:209], v[74:77]
	v_mfma_f32_16x16x32_bf16 v[118:121], v[164:167], v[182:185], v[118:121]
	v_mfma_f32_16x16x32_bf16 v[114:117], v[172:175], v[182:185], v[114:117]
	v_mfma_f32_16x16x32_bf16 v[102:105], v[164:167], v[190:193], v[102:105]
	v_mfma_f32_16x16x32_bf16 v[98:101], v[172:175], v[190:193], v[98:101]
	v_mfma_f32_16x16x32_bf16 v[86:89], v[164:167], v[198:201], v[86:89]
	v_mfma_f32_16x16x32_bf16 v[82:85], v[172:175], v[198:201], v[82:85]
	v_mfma_f32_16x16x32_bf16 v[70:73], v[164:167], v[206:209], v[70:73]
	v_mfma_f32_16x16x32_bf16 v[66:69], v[172:175], v[206:209], v[66:69]
	v_mfma_f32_16x16x32_bf16 v[126:129], v[152:155], v[186:189], v[126:129]
	v_mfma_f32_16x16x32_bf16 v[122:125], v[160:163], v[186:189], v[122:125]
	v_mfma_f32_16x16x32_bf16 v[110:113], v[152:155], v[194:197], v[110:113]
	v_mfma_f32_16x16x32_bf16 v[106:109], v[160:163], v[194:197], v[106:109]
	v_mfma_f32_16x16x32_bf16 v[94:97], v[152:155], v[202:205], v[94:97]
	v_mfma_f32_16x16x32_bf16 v[90:93], v[160:163], v[202:205], v[90:93]
	v_mfma_f32_16x16x32_bf16 v[78:81], v[152:155], v[210:213], v[78:81]
	v_mfma_f32_16x16x32_bf16 v[74:77], v[160:163], v[210:213], v[74:77]
	v_mfma_f32_16x16x32_bf16 v[118:121], v[168:171], v[186:189], v[118:121]
	v_mfma_f32_16x16x32_bf16 v[114:117], v[176:179], v[186:189], v[114:117]
	v_mfma_f32_16x16x32_bf16 v[102:105], v[168:171], v[194:197], v[102:105]
	v_mfma_f32_16x16x32_bf16 v[98:101], v[176:179], v[194:197], v[98:101]
	v_mfma_f32_16x16x32_bf16 v[86:89], v[168:171], v[202:205], v[86:89]
	v_mfma_f32_16x16x32_bf16 v[82:85], v[176:179], v[202:205], v[82:85]
	v_mfma_f32_16x16x32_bf16 v[70:73], v[168:171], v[210:213], v[70:73]
	v_mfma_f32_16x16x32_bf16 v[66:69], v[176:179], v[210:213], v[66:69]
	s_setprio 0
	s_barrier
; #define PG8_STAGE(bufoff, gbase, voff) do { _Pragma("unroll") for (int _i = 0; _i < 2; ++_i) \
;         __builtin_amdgcn_global_load_lds((const unsigned*)((const char*)(gbase) + (voff)[_i]), (LAS unsigned*)(lds + (bufoff) + ldsw + _i * 8192), 16, 0, 0); } while (0)
; #define PG8_LDA(dst, b, h) do { _Pragma("unroll") for (int m = 0; m < 4; ++m) _Pragma("unroll") for (int k = 0; k < 2; ++k) dst[m][k] = *(const LAS bf16x8*)(lds + PG8_SA(b, h) + aoff + m * 2048 + k * 1024); } while (0)
; #define PG8_MMA(ai, bj, At, Bt) do { __builtin_amdgcn_s_setprio(1); _Pragma("unroll") for (int m = 0; m < 4; ++m) _Pragma("unroll") for (int n = 0; n < 2; ++n) _Pragma("unroll") for (int k = 0; k < 2; ++k) \
;         acc[ai][bj][m][n] = __builtin_amdgcn_mfma_f32_16x16x32_bf16(Bt[n][k], At[m][k], acc[ai][bj][m][n], 0, 0, 0); __builtin_amdgcn_s_setprio(0); } while (0)
; #define PG8_WAIT_V(n) asm volatile("s_waitcnt vmcnt(" #n ")" ::: "memory")
; #define PG8_WAIT_L(n) asm volatile("s_waitcnt lgkmcnt(" #n ")" ::: "memory")
; #define PG8_BAR __builtin_amdgcn_s_barrier()
; #define PG8_SCHED __builtin_amdgcn_sched_barrier(0)
; template <class Epi>
; __device__ __forceinline__ void gemm_phase(LAS unsigned char* lds, const Gemm g, const StaticOrder& S, const Epi& E) {
;     ...
;             PG8_LDA(At, 1, 1); PG8_STAGE(PG8_SB(1, 0), b3, voffB); PG8_STAGE(PG8_SB(1, 1), b3 + hB, voffB); PG8_STAGE(PG8_SA(1, 0), a3, voffA);
;             PG8_WAIT_V(8); PG8_WAIT_L(0); PG8_BAR; PG8_MMA(1, 0, At, B0); PG8_MMA(1, 1, At, B1); PG8_BAR; PG8_SCHED;
;         }
	s_add_i32 s24, s51, s31
	v_lshl_add_u64 v[214:215], v[214:215], 0, s[88:89]
	s_mov_b32 m0, s24
	ds_read_b128 v[182:185], v147 offset:49152
	ds_read_b128 v[186:189], v147 offset:50176
	ds_read_b128 v[190:193], v147 offset:51200
	ds_read_b128 v[194:197], v147 offset:52224
	ds_read_b128 v[198:201], v147 offset:53248
	ds_read_b128 v[202:205], v147 offset:54272
	ds_read_b128 v[206:209], v147 offset:55296
	ds_read_b128 v[210:213], v147 offset:56320
	global_load_lds_dwordx4 v[214:215], off
	s_add_i32 m0, s24, 0x2000
	s_add_u32 s22, s22, 0x40080
	v_lshl_add_u64 v[214:215], v[216:217], 0, s[88:89]
	s_addc_u32 s23, s23, 0
	s_add_i32 s24, s52, s31
	global_load_lds_dwordx4 v[214:215], off
	v_lshl_add_u64 v[214:215], s[22:23], 0, v[134:135]
	s_mov_b32 m0, s24
	s_nop 0
	global_load_lds_dwordx4 v[214:215], off
	v_lshl_add_u64 v[214:215], s[22:23], 0, v[130:131]
	s_add_i32 m0, s24, 0x2000
	s_nop 0
	global_load_lds_dwordx4 v[214:215], off
	v_lshl_add_u64 v[214:215], v[218:219], 0, s[88:89]
	s_mov_b32 m0, s38
	s_nop 0
	global_load_lds_dwordx4 v[214:215], off
	v_lshl_add_u64 v[214:215], v[220:221], 0, s[88:89]
	s_mov_b32 m0, s39
	s_nop 0
	global_load_lds_dwordx4 v[214:215], off
	s_waitcnt vmcnt(8)
	s_waitcnt lgkmcnt(0)
	s_barrier
	s_setprio 1
	v_mfma_f32_16x16x32_bf16 v[62:65], v[148:151], v[182:185], v[62:65]
	v_mfma_f32_16x16x32_bf16 v[58:61], v[156:159], v[182:185], v[58:61]
	v_mfma_f32_16x16x32_bf16 v[46:49], v[148:151], v[190:193], v[46:49]
	v_mfma_f32_16x16x32_bf16 v[42:45], v[156:159], v[190:193], v[42:45]
	v_mfma_f32_16x16x32_bf16 v[30:33], v[148:151], v[198:201], v[30:33]
	v_mfma_f32_16x16x32_bf16 v[26:29], v[156:159], v[198:201], v[26:29]
	v_mfma_f32_16x16x32_bf16 v[14:17], v[148:151], v[206:209], v[14:17]
	v_mfma_f32_16x16x32_bf16 v[10:13], v[156:159], v[206:209], v[10:13]
	v_mfma_f32_16x16x32_bf16 v[54:57], v[164:167], v[182:185], v[54:57]
	v_mfma_f32_16x16x32_bf16 v[50:53], v[172:175], v[182:185], v[50:53]
	v_mfma_f32_16x16x32_bf16 v[38:41], v[164:167], v[190:193], v[38:41]
	v_mfma_f32_16x16x32_bf16 v[34:37], v[172:175], v[190:193], v[34:37]
	v_mfma_f32_16x16x32_bf16 v[22:25], v[164:167], v[198:201], v[22:25]
	v_mfma_f32_16x16x32_bf16 v[18:21], v[172:175], v[198:201], v[18:21]
	v_mfma_f32_16x16x32_bf16 v[6:9], v[164:167], v[206:209], v[6:9]
	v_mfma_f32_16x16x32_bf16 v[2:5], v[172:175], v[206:209], v[2:5]
	v_mfma_f32_16x16x32_bf16 v[62:65], v[152:155], v[186:189], v[62:65]
	v_mfma_f32_16x16x32_bf16 v[58:61], v[160:163], v[186:189], v[58:61]
	v_mfma_f32_16x16x32_bf16 v[46:49], v[152:155], v[194:197], v[46:49]
	v_mfma_f32_16x16x32_bf16 v[42:45], v[160:163], v[194:197], v[42:45]
	v_mfma_f32_16x16x32_bf16 v[30:33], v[152:155], v[202:205], v[30:33]
	v_mfma_f32_16x16x32_bf16 v[26:29], v[160:163], v[202:205], v[26:29]
	v_mfma_f32_16x16x32_bf16 v[14:17], v[152:155], v[210:213], v[14:17]
	v_mfma_f32_16x16x32_bf16 v[10:13], v[160:163], v[210:213], v[10:13]
	v_mfma_f32_16x16x32_bf16 v[54:57], v[168:171], v[186:189], v[54:57]
	v_mfma_f32_16x16x32_bf16 v[50:53], v[176:179], v[186:189], v[50:53]
	v_mfma_f32_16x16x32_bf16 v[38:41], v[168:171], v[194:197], v[38:41]
	v_mfma_f32_16x16x32_bf16 v[34:37], v[176:179], v[194:197], v[34:37]
	v_mfma_f32_16x16x32_bf16 v[22:25], v[168:171], v[202:205], v[22:25]
	v_mfma_f32_16x16x32_bf16 v[18:21], v[176:179], v[202:205], v[18:21]
	v_mfma_f32_16x16x32_bf16 v[6:9], v[168:171], v[210:213], v[6:9]
	v_mfma_f32_16x16x32_bf16 v[2:5], v[176:179], v[210:213], v[2:5]
	s_setprio 0
	s_barrier
	s_add_i32 s50, s50, 2
	s_add_u32 s20, s20, 0x100
	s_addc_u32 s21, s21, 0
	s_add_u32 s48, s48, 0x100
	s_addc_u32 s49, s49, 0
	s_cmp_gt_u32 s50, 13
	s_cbranch_scc0 .LBB0_1550
	s_and_b64 vcc, exec, s[10:11]
	s_cbranch_vccz .LBB0_1553
	s_barrier

; #define PG8_STAGE(bufoff, gbase, voff) do { _Pragma("unroll") for (int _i = 0; _i < 2; ++_i) \
;         __builtin_amdgcn_global_load_lds((const unsigned*)((const char*)(gbase) + (voff)[_i]), (LAS unsigned*)(lds + (bufoff) + ldsw + _i * 8192), 16, 0, 0); } while (0)
; #define PG8_LDA(dst, b, h) do { _Pragma("unroll") for (int m = 0; m < 4; ++m) _Pragma("unroll") for (int k = 0; k < 2; ++k) dst[m][k] = *(const LAS bf16x8*)(lds + PG8_SA(b, h) + aoff + m * 2048 + k * 1024); } while (0)
; #define PG8_LDB(dst, b, h) do { _Pragma("unroll") for (int n = 0; n < 2; ++n) _Pragma("unroll") for (int k = 0; k < 2; ++k) dst[n][k] = *(const LAS bf16x8*)(lds + PG8_SB(b, h) + boff + n * 2048 + k * 1024); } while (0)
; #define PG8_MMA(ai, bj, At, Bt) do { __builtin_amdgcn_s_setprio(1); _Pragma("unroll") for (int m = 0; m < 4; ++m) _Pragma("unroll") for (int n = 0; n < 2; ++n) _Pragma("unroll") for (int k = 0; k < 2; ++k) \
;         acc[ai][bj][m][n] = __builtin_amdgcn_mfma_f32_16x16x32_bf16(Bt[n][k], At[m][k], acc[ai][bj][m][n], 0, 0, 0); __builtin_amdgcn_s_setprio(0); } while (0)
; #define PG8_WAIT_V(n) asm volatile("s_waitcnt vmcnt(" #n ")" ::: "memory")
; #define PG8_WAIT_L(n) asm volatile("s_waitcnt lgkmcnt(" #n ")" ::: "memory")
; #define PG8_BAR __builtin_amdgcn_s_barrier()
; #define PG8_SCHED __builtin_amdgcn_sched_barrier(0)
; template <class Epi>
; __device__ __forceinline__ void gemm_phase(LAS unsigned char* lds, const Gemm g, const StaticOrder& S, const Epi& E) {
;     ...
;             const bool last = (t == nt - 2);
;             const char* a1 = cA + (size_t)(t + 1) * kstep;
;             const char* a2 = last ? nA : cA + (size_t)(t + 2) * kstep; const char* b2 = last ? nB : cB + (size_t)(t + 2) * kstep;
;             const char* a3 = a2 + kstep; const char* b3 = b2 + kstep;
;             PG8_LDB(B0, 0, 0); PG8_LDB(B1, 0, 1); PG8_SCHED; PG8_LDA(At, 0, 0); PG8_STAGE(PG8_SA(1, 1), a1 + hA, voffA);
;             PG8_WAIT_V(8); PG8_WAIT_L(0); PG8_BAR; PG8_MMA(0, 0, At, B0); PG8_MMA(0, 1, At, B1); PG8_BAR; PG8_SCHED;
;             PG8_LDA(At, 0, 1); PG8_STAGE(PG8_SB(0, 0), b2, voffB); PG8_STAGE(PG8_SB(0, 1), b2 + hB, voffB); PG8_STAGE(PG8_SA(0, 0), a2, voffA);
;             PG8_WAIT_V(8); PG8_WAIT_L(0); PG8_BAR; PG8_MMA(1, 0, At, B0); PG8_MMA(1, 1, At, B1); PG8_BAR; PG8_SCHED;
.LBB0_1632:
	s_add_u32 s8, s10, 0x100
	s_addc_u32 s9, s11, 0
	s_add_i32 s70, 0, 0x10000
	s_cmp_eq_u32 s67, 40
	s_cselect_b32 s45, s39, s9
	s_cselect_b32 s44, s38, s8
	s_cselect_b32 s43, s41, s37
	s_cselect_b32 s42, s40, s35
	s_add_i32 s71, 0, 0x14000
	s_waitcnt lgkmcnt(0)
	v_add_u32_e32 v158, s70, v180
	v_add_u32_e32 v174, s71, v180
	ds_read_b128 v[146:149], v158
	ds_read_b128 v[150:153], v158 offset:1024
	ds_read_b128 v[154:157], v158 offset:2048
	ds_read_b128 v[158:161], v158 offset:3072
	ds_read_b128 v[162:165], v174
	ds_read_b128 v[166:169], v174 offset:1024
	ds_read_b128 v[170:173], v174 offset:2048
	ds_read_b128 v[174:177], v174 offset:3072
	v_lshl_add_u64 v[178:179], s[10:11], 0, v[142:143]
	s_add_i32 m0, s52, 0xc000
	ds_read_b128 v[182:185], v192
	ds_read_b128 v[196:199], v192 offset:1024
	ds_read_b128 v[200:203], v192 offset:2048
	ds_read_b128 v[204:207], v192 offset:3072
	ds_read_b128 v[208:211], v192 offset:4096
	ds_read_b128 v[212:215], v192 offset:5120
	ds_read_b128 v[216:219], v192 offset:6144
	ds_read_b128 v[232:235], v192 offset:7168
	global_load_lds_dwordx4 v[178:179], off
	v_lshl_add_u64 v[178:179], s[10:11], 0, v[144:145]
	s_add_i32 m0, s52, 0xe000
	s_nop 0
	global_load_lds_dwordx4 v[178:179], off
	s_waitcnt vmcnt(8)
	s_waitcnt lgkmcnt(0)
	s_barrier
	s_setprio 1
	v_mfma_f32_16x16x32_bf16 v[26:29], v[146:149], v[182:185], v[26:29]
	v_mfma_f32_16x16x32_bf16 v[30:33], v[154:157], v[182:185], v[30:33]
	v_mfma_f32_16x16x32_bf16 v[58:61], v[146:149], v[200:203], v[58:61]
	v_mfma_f32_16x16x32_bf16 v[62:65], v[154:157], v[200:203], v[62:65]
	v_mfma_f32_16x16x32_bf16 v[90:93], v[146:149], v[208:211], v[90:93]
	v_mfma_f32_16x16x32_bf16 v[94:97], v[154:157], v[208:211], v[94:97]
	v_mfma_f32_16x16x32_bf16 v[114:117], v[146:149], v[216:219], v[114:117]
	v_mfma_f32_16x16x32_bf16 v[118:121], v[154:157], v[216:219], v[118:121]
	v_mfma_f32_16x16x32_bf16 v[42:45], v[162:165], v[182:185], v[42:45]
	v_mfma_f32_16x16x32_bf16 v[46:49], v[170:173], v[182:185], v[46:49]
	v_mfma_f32_16x16x32_bf16 v[74:77], v[162:165], v[200:203], v[74:77]
	v_mfma_f32_16x16x32_bf16 v[78:81], v[170:173], v[200:203], v[78:81]
	v_mfma_f32_16x16x32_bf16 v[106:109], v[162:165], v[208:211], v[106:109]
	v_mfma_f32_16x16x32_bf16 v[110:113], v[170:173], v[208:211], v[110:113]
	v_mfma_f32_16x16x32_bf16 v[126:129], v[162:165], v[216:219], v[126:129]
	v_mfma_f32_16x16x32_bf16 v[122:125], v[170:173], v[216:219], v[122:125]
	v_mfma_f32_16x16x32_bf16 v[26:29], v[150:153], v[196:199], v[26:29]
	v_mfma_f32_16x16x32_bf16 v[30:33], v[158:161], v[196:199], v[30:33]
	v_mfma_f32_16x16x32_bf16 v[58:61], v[150:153], v[204:207], v[58:61]
	v_mfma_f32_16x16x32_bf16 v[62:65], v[158:161], v[204:207], v[62:65]
	v_mfma_f32_16x16x32_bf16 v[90:93], v[150:153], v[212:215], v[90:93]
	v_mfma_f32_16x16x32_bf16 v[94:97], v[158:161], v[212:215], v[94:97]
	v_mfma_f32_16x16x32_bf16 v[114:117], v[150:153], v[232:235], v[114:117]
	v_mfma_f32_16x16x32_bf16 v[118:121], v[158:161], v[232:235], v[118:121]
	v_mfma_f32_16x16x32_bf16 v[42:45], v[166:169], v[196:199], v[42:45]
	v_mfma_f32_16x16x32_bf16 v[46:49], v[174:177], v[196:199], v[46:49]
	v_mfma_f32_16x16x32_bf16 v[74:77], v[166:169], v[204:207], v[74:77]
	v_mfma_f32_16x16x32_bf16 v[78:81], v[174:177], v[204:207], v[78:81]
	v_mfma_f32_16x16x32_bf16 v[106:109], v[166:169], v[212:215], v[106:109]
	v_mfma_f32_16x16x32_bf16 v[110:113], v[174:177], v[212:215], v[110:113]
	v_mfma_f32_16x16x32_bf16 v[126:129], v[166:169], v[232:235], v[126:129]
	v_mfma_f32_16x16x32_bf16 v[122:125], v[174:177], v[232:235], v[122:125]
	s_setprio 0
	s_barrier
	s_add_i32 s10, s70, s47
	v_lshl_add_u64 v[178:179], s[42:43], 0, v[132:133]
	s_mov_b32 m0, s10
	ds_read_b128 v[182:185], v192 offset:16384
	ds_read_b128 v[196:199], v192 offset:17408
	ds_read_b128 v[200:203], v192 offset:18432
	ds_read_b128 v[204:207], v192 offset:19456
	ds_read_b128 v[208:211], v192 offset:20480
	ds_read_b128 v[212:215], v192 offset:21504
	ds_read_b128 v[216:219], v192 offset:22528
	ds_read_b128 v[232:235], v192 offset:23552
	global_load_lds_dwordx4 v[178:179], off
	s_add_i32 m0, s10, 0x2000
	s_add_u32 s10, s42, 0xb0000
	v_lshl_add_u64 v[186:187], s[42:43], 0, v[136:137]
	s_addc_u32 s11, s43, 0
	s_add_i32 s70, s71, s47
	global_load_lds_dwordx4 v[186:187], off
	v_lshl_add_u64 v[220:221], s[10:11], 0, v[132:133]
	s_mov_b32 m0, s70
	v_lshl_add_u64 v[236:237], s[44:45], 0, v[134:135]
	global_load_lds_dwordx4 v[220:221], off
	v_lshl_add_u64 v[220:221], s[10:11], 0, v[136:137]
	s_add_i32 m0, s70, 0x2000
	s_nop 0
	global_load_lds_dwordx4 v[220:221], off
	v_lshl_add_u64 v[220:221], s[44:45], 0, v[130:131]
	s_mov_b32 m0, s52
	s_nop 0
	global_load_lds_dwordx4 v[220:221], off
	s_mov_b32 m0, s53
	s_nop 0
	global_load_lds_dwordx4 v[236:237], off
	s_waitcnt vmcnt(8)
	s_waitcnt lgkmcnt(0)
	s_barrier
; #define PG8_STAGE(bufoff, gbase, voff) do { _Pragma("unroll") for (int _i = 0; _i < 2; ++_i) \
;         __builtin_amdgcn_global_load_lds((const unsigned*)((const char*)(gbase) + (voff)[_i]), (LAS unsigned*)(lds + (bufoff) + ldsw + _i * 8192), 16, 0, 0); } while (0)
; #define PG8_LDA(dst, b, h) do { _Pragma("unroll") for (int m = 0; m < 4; ++m) _Pragma("unroll") for (int k = 0; k < 2; ++k) dst[m][k] = *(const LAS bf16x8*)(lds + PG8_SA(b, h) + aoff + m * 2048 + k * 1024); } while (0)
; #define PG8_LDB(dst, b, h) do { _Pragma("unroll") for (int n = 0; n < 2; ++n) _Pragma("unroll") for (int k = 0; k < 2; ++k) dst[n][k] = *(const LAS bf16x8*)(lds + PG8_SB(b, h) + boff + n * 2048 + k * 1024); } while (0)
; #define PG8_MMA(ai, bj, At, Bt) do { __builtin_amdgcn_s_setprio(1); _Pragma("unroll") for (int m = 0; m < 4; ++m) _Pragma("unroll") for (int n = 0; n < 2; ++n) _Pragma("unroll") for (int k = 0; k < 2; ++k) \
;         acc[ai][bj][m][n] = __builtin_amdgcn_mfma_f32_16x16x32_bf16(Bt[n][k], At[m][k], acc[ai][bj][m][n], 0, 0, 0); __builtin_amdgcn_s_setprio(0); } while (0)
; #define PG8_WAIT_V(n) asm volatile("s_waitcnt vmcnt(" #n ")" ::: "memory")
; #define PG8_WAIT_L(n) asm volatile("s_waitcnt lgkmcnt(" #n ")" ::: "memory")
; #define PG8_BAR __builtin_amdgcn_s_barrier()
; #define PG8_SCHED __builtin_amdgcn_sched_barrier(0)
; template <class Epi>
; __device__ __forceinline__ void gemm_phase(LAS unsigned char* lds, const Gemm g, const StaticOrder& S, const Epi& E) {
;     ...
;             PG8_WAIT_V(8); PG8_WAIT_L(0); PG8_BAR; PG8_MMA(1, 0, At, B0); PG8_MMA(1, 1, At, B1); PG8_BAR; PG8_SCHED;
;             PG8_LDB(B0, 1, 0); PG8_LDB(B1, 1, 1); PG8_SCHED; PG8_LDA(At, 1, 0); PG8_STAGE(PG8_SA(0, 1), a2 + hA, voffA);
;             PG8_WAIT_V(8); PG8_WAIT_L(0); PG8_BAR; PG8_MMA(0, 0, At, B0); PG8_MMA(0, 1, At, B1); PG8_BAR; PG8_SCHED;
	s_setprio 1
	v_mfma_f32_16x16x32_bf16 v[102:105], v[146:149], v[182:185], v[102:105]
	v_mfma_f32_16x16x32_bf16 v[98:101], v[154:157], v[182:185], v[98:101]
	v_mfma_f32_16x16x32_bf16 v[70:73], v[146:149], v[200:203], v[70:73]
	v_mfma_f32_16x16x32_bf16 v[66:69], v[154:157], v[200:203], v[66:69]
	v_mfma_f32_16x16x32_bf16 v[38:41], v[146:149], v[208:211], v[38:41]
	v_mfma_f32_16x16x32_bf16 v[34:37], v[154:157], v[208:211], v[34:37]
	v_mfma_f32_16x16x32_bf16 v[14:17], v[146:149], v[216:219], v[14:17]
	v_mfma_f32_16x16x32_bf16 v[10:13], v[154:157], v[216:219], v[10:13]
	v_mfma_f32_16x16x32_bf16 v[86:89], v[162:165], v[182:185], v[86:89]
	v_mfma_f32_16x16x32_bf16 v[82:85], v[170:173], v[182:185], v[82:85]
	v_mfma_f32_16x16x32_bf16 v[54:57], v[162:165], v[200:203], v[54:57]
	v_mfma_f32_16x16x32_bf16 v[50:53], v[170:173], v[200:203], v[50:53]
	v_mfma_f32_16x16x32_bf16 v[22:25], v[162:165], v[208:211], v[22:25]
	v_mfma_f32_16x16x32_bf16 v[18:21], v[170:173], v[208:211], v[18:21]
	v_mfma_f32_16x16x32_bf16 v[6:9], v[162:165], v[216:219], v[6:9]
	v_mfma_f32_16x16x32_bf16 v[2:5], v[170:173], v[216:219], v[2:5]
	v_mfma_f32_16x16x32_bf16 v[102:105], v[150:153], v[196:199], v[102:105]
	v_mfma_f32_16x16x32_bf16 v[98:101], v[158:161], v[196:199], v[98:101]
	v_mfma_f32_16x16x32_bf16 v[70:73], v[150:153], v[204:207], v[70:73]
	v_mfma_f32_16x16x32_bf16 v[66:69], v[158:161], v[204:207], v[66:69]
	v_mfma_f32_16x16x32_bf16 v[38:41], v[150:153], v[212:215], v[38:41]
	v_mfma_f32_16x16x32_bf16 v[34:37], v[158:161], v[212:215], v[34:37]
	v_mfma_f32_16x16x32_bf16 v[14:17], v[150:153], v[232:235], v[14:17]
	v_mfma_f32_16x16x32_bf16 v[10:13], v[158:161], v[232:235], v[10:13]
	v_mfma_f32_16x16x32_bf16 v[86:89], v[166:169], v[196:199], v[86:89]
	v_mfma_f32_16x16x32_bf16 v[82:85], v[174:177], v[196:199], v[82:85]
	v_mfma_f32_16x16x32_bf16 v[54:57], v[166:169], v[204:207], v[54:57]
	v_mfma_f32_16x16x32_bf16 v[50:53], v[174:177], v[204:207], v[50:53]
	v_mfma_f32_16x16x32_bf16 v[22:25], v[166:169], v[212:215], v[22:25]
	v_mfma_f32_16x16x32_bf16 v[18:21], v[174:177], v[212:215], v[18:21]
	v_mfma_f32_16x16x32_bf16 v[6:9], v[166:169], v[232:235], v[6:9]
	v_mfma_f32_16x16x32_bf16 v[2:5], v[174:177], v[232:235], v[2:5]
	s_setprio 0
	s_barrier
	s_add_i32 s70, 0, 0x18000
	s_add_i32 s71, 0, 0x1c000
	v_add_u32_e32 v158, s70, v180
	v_add_u32_e32 v174, s71, v180
	ds_read_b128 v[146:149], v158
	ds_read_b128 v[150:153], v158 offset:1024
	ds_read_b128 v[154:157], v158 offset:2048
	ds_read_b128 v[158:161], v158 offset:3072
	ds_read_b128 v[162:165], v174
	ds_read_b128 v[166:169], v174 offset:1024
	ds_read_b128 v[170:173], v174 offset:2048
	ds_read_b128 v[174:177], v174 offset:3072
	s_add_u32 s10, s44, 0xb0000
	s_addc_u32 s11, s45, 0
	s_mov_b32 m0, s54
	v_lshl_add_u64 v[238:239], s[10:11], 0, v[130:131]
	ds_read_b128 v[182:185], v192 offset:32768
	ds_read_b128 v[196:199], v192 offset:33792
	ds_read_b128 v[200:203], v192 offset:34816
	ds_read_b128 v[204:207], v192 offset:35840
	ds_read_b128 v[208:211], v192 offset:36864
	ds_read_b128 v[212:215], v192 offset:37888
	ds_read_b128 v[216:219], v192 offset:38912
	ds_read_b128 v[232:235], v192 offset:39936
	global_load_lds_dwordx4 v[238:239], off
	v_lshl_add_u64 v[238:239], s[10:11], 0, v[134:135]
	s_mov_b32 m0, s55
	s_nop 0
	global_load_lds_dwordx4 v[238:239], off
	s_waitcnt vmcnt(8)
	s_waitcnt lgkmcnt(0)
	s_barrier
	s_setprio 1
	v_mfma_f32_16x16x32_bf16 v[26:29], v[146:149], v[182:185], v[26:29]
	v_mfma_f32_16x16x32_bf16 v[30:33], v[154:157], v[182:185], v[30:33]
	v_mfma_f32_16x16x32_bf16 v[58:61], v[146:149], v[200:203], v[58:61]
	v_mfma_f32_16x16x32_bf16 v[62:65], v[154:157], v[200:203], v[62:65]
	v_mfma_f32_16x16x32_bf16 v[90:93], v[146:149], v[208:211], v[90:93]
	v_mfma_f32_16x16x32_bf16 v[94:97], v[154:157], v[208:211], v[94:97]
	v_mfma_f32_16x16x32_bf16 v[114:117], v[146:149], v[216:219], v[114:117]
	v_mfma_f32_16x16x32_bf16 v[118:121], v[154:157], v[216:219], v[118:121]
	v_mfma_f32_16x16x32_bf16 v[42:45], v[162:165], v[182:185], v[42:45]
	v_mfma_f32_16x16x32_bf16 v[46:49], v[170:173], v[182:185], v[46:49]
	v_mfma_f32_16x16x32_bf16 v[74:77], v[162:165], v[200:203], v[74:77]
	v_mfma_f32_16x16x32_bf16 v[78:81], v[170:173], v[200:203], v[78:81]
	v_mfma_f32_16x16x32_bf16 v[106:109], v[162:165], v[208:211], v[106:109]
	v_mfma_f32_16x16x32_bf16 v[110:113], v[170:173], v[208:211], v[110:113]
	v_mfma_f32_16x16x32_bf16 v[126:129], v[162:165], v[216:219], v[126:129]
	v_mfma_f32_16x16x32_bf16 v[122:125], v[170:173], v[216:219], v[122:125]
	v_mfma_f32_16x16x32_bf16 v[26:29], v[150:153], v[196:199], v[26:29]
	v_mfma_f32_16x16x32_bf16 v[30:33], v[158:161], v[196:199], v[30:33]
	v_mfma_f32_16x16x32_bf16 v[58:61], v[150:153], v[204:207], v[58:61]
	v_mfma_f32_16x16x32_bf16 v[62:65], v[158:161], v[204:207], v[62:65]
	v_mfma_f32_16x16x32_bf16 v[90:93], v[150:153], v[212:215], v[90:93]
	v_mfma_f32_16x16x32_bf16 v[94:97], v[158:161], v[212:215], v[94:97]
	v_mfma_f32_16x16x32_bf16 v[114:117], v[150:153], v[232:235], v[114:117]
	v_mfma_f32_16x16x32_bf16 v[118:121], v[158:161], v[232:235], v[118:121]
	v_mfma_f32_16x16x32_bf16 v[42:45], v[166:169], v[196:199], v[42:45]
	v_mfma_f32_16x16x32_bf16 v[46:49], v[174:177], v[196:199], v[46:49]
	v_mfma_f32_16x16x32_bf16 v[74:77], v[166:169], v[204:207], v[74:77]
	v_mfma_f32_16x16x32_bf16 v[78:81], v[174:177], v[204:207], v[78:81]
	v_mfma_f32_16x16x32_bf16 v[106:109], v[166:169], v[212:215], v[106:109]
	v_mfma_f32_16x16x32_bf16 v[110:113], v[174:177], v[212:215], v[110:113]
	v_mfma_f32_16x16x32_bf16 v[126:129], v[166:169], v[232:235], v[126:129]
	v_mfma_f32_16x16x32_bf16 v[122:125], v[174:177], v[232:235], v[122:125]
	s_setprio 0
	s_barrier
; #define PG8_STAGE(bufoff, gbase, voff) do { _Pragma("unroll") for (int _i = 0; _i < 2; ++_i) \
;         __builtin_amdgcn_global_load_lds((const unsigned*)((const char*)(gbase) + (voff)[_i]), (LAS unsigned*)(lds + (bufoff) + ldsw + _i * 8192), 16, 0, 0); } while (0)
; #define PG8_LDA(dst, b, h) do { _Pragma("unroll") for (int m = 0; m < 4; ++m) _Pragma("unroll") for (int k = 0; k < 2; ++k) dst[m][k] = *(const LAS bf16x8*)(lds + PG8_SA(b, h) + aoff + m * 2048 + k * 1024); } while (0)
; #define PG8_MMA(ai, bj, At, Bt) do { __builtin_amdgcn_s_setprio(1); _Pragma("unroll") for (int m = 0; m < 4; ++m) _Pragma("unroll") for (int n = 0; n < 2; ++n) _Pragma("unroll") for (int k = 0; k < 2; ++k) \
;         acc[ai][bj][m][n] = __builtin_amdgcn_mfma_f32_16x16x32_bf16(Bt[n][k], At[m][k], acc[ai][bj][m][n], 0, 0, 0); __builtin_amdgcn_s_setprio(0); } while (0)
; #define PG8_WAIT_V(n) asm volatile("s_waitcnt vmcnt(" #n ")" ::: "memory")
; #define PG8_WAIT_L(n) asm volatile("s_waitcnt lgkmcnt(" #n ")" ::: "memory")
; #define PG8_BAR __builtin_amdgcn_s_barrier()
; #define PG8_SCHED __builtin_amdgcn_sched_barrier(0)
; template <class Epi>
; __device__ __forceinline__ void gemm_phase(LAS unsigned char* lds, const Gemm g, const StaticOrder& S, const Epi& E) {
;     ...
;             PG8_LDA(At, 1, 1); PG8_STAGE(PG8_SB(1, 0), b3, voffB); PG8_STAGE(PG8_SB(1, 1), b3 + hB, voffB); PG8_STAGE(PG8_SA(1, 0), a3, voffA);
;             PG8_WAIT_V(8); PG8_WAIT_L(0); PG8_BAR; PG8_MMA(1, 0, At, B0); PG8_MMA(1, 1, At, B1); PG8_BAR; PG8_SCHED;
;         }
	s_add_i32 s10, s70, s47
	v_lshl_add_u64 v[178:179], v[178:179], 0, s[88:89]
	s_mov_b32 m0, s10
	ds_read_b128 v[182:185], v192 offset:49152
	ds_read_b128 v[196:199], v192 offset:50176
	ds_read_b128 v[200:203], v192 offset:51200
	ds_read_b128 v[204:207], v192 offset:52224
	ds_read_b128 v[208:211], v192 offset:53248
	ds_read_b128 v[212:215], v192 offset:54272
	ds_read_b128 v[216:219], v192 offset:55296
	ds_read_b128 v[232:235], v192 offset:56320
	global_load_lds_dwordx4 v[178:179], off
	s_add_i32 m0, s10, 0x2000
	s_add_u32 s10, s42, 0xb0080
	v_lshl_add_u64 v[178:179], v[186:187], 0, s[88:89]
	s_addc_u32 s11, s43, 0
	s_add_i32 s42, s71, s47
	global_load_lds_dwordx4 v[178:179], off
	v_lshl_add_u64 v[178:179], s[10:11], 0, v[132:133]
	s_mov_b32 m0, s42
	s_nop 0
	global_load_lds_dwordx4 v[178:179], off
	v_lshl_add_u64 v[178:179], s[10:11], 0, v[136:137]
	s_add_i32 m0, s42, 0x2000
	s_nop 0
	global_load_lds_dwordx4 v[178:179], off
	v_lshl_add_u64 v[178:179], v[220:221], 0, s[88:89]
	s_mov_b32 m0, s56
	s_nop 0
	global_load_lds_dwordx4 v[178:179], off
	v_lshl_add_u64 v[178:179], v[236:237], 0, s[88:89]
	s_mov_b32 m0, s57
	s_nop 0
	global_load_lds_dwordx4 v[178:179], off
	s_waitcnt vmcnt(8)
	s_waitcnt lgkmcnt(0)
	s_barrier
	s_setprio 1
	v_mfma_f32_16x16x32_bf16 v[102:105], v[146:149], v[182:185], v[102:105]
	v_mfma_f32_16x16x32_bf16 v[98:101], v[154:157], v[182:185], v[98:101]
	v_mfma_f32_16x16x32_bf16 v[70:73], v[146:149], v[200:203], v[70:73]
	v_mfma_f32_16x16x32_bf16 v[66:69], v[154:157], v[200:203], v[66:69]
	v_mfma_f32_16x16x32_bf16 v[38:41], v[146:149], v[208:211], v[38:41]
	v_mfma_f32_16x16x32_bf16 v[34:37], v[154:157], v[208:211], v[34:37]
	v_mfma_f32_16x16x32_bf16 v[14:17], v[146:149], v[216:219], v[14:17]
	v_mfma_f32_16x16x32_bf16 v[10:13], v[154:157], v[216:219], v[10:13]
	v_mfma_f32_16x16x32_bf16 v[86:89], v[162:165], v[182:185], v[86:89]
	v_mfma_f32_16x16x32_bf16 v[82:85], v[170:173], v[182:185], v[82:85]
	v_mfma_f32_16x16x32_bf16 v[54:57], v[162:165], v[200:203], v[54:57]
	v_mfma_f32_16x16x32_bf16 v[50:53], v[170:173], v[200:203], v[50:53]
	v_mfma_f32_16x16x32_bf16 v[22:25], v[162:165], v[208:211], v[22:25]
	v_mfma_f32_16x16x32_bf16 v[18:21], v[170:173], v[208:211], v[18:21]
	v_mfma_f32_16x16x32_bf16 v[6:9], v[162:165], v[216:219], v[6:9]
	v_mfma_f32_16x16x32_bf16 v[2:5], v[170:173], v[216:219], v[2:5]
	v_mfma_f32_16x16x32_bf16 v[102:105], v[150:153], v[196:199], v[102:105]
	v_mfma_f32_16x16x32_bf16 v[98:101], v[158:161], v[196:199], v[98:101]
	v_mfma_f32_16x16x32_bf16 v[70:73], v[150:153], v[204:207], v[70:73]
	v_mfma_f32_16x16x32_bf16 v[66:69], v[158:161], v[204:207], v[66:69]
	v_mfma_f32_16x16x32_bf16 v[38:41], v[150:153], v[212:215], v[38:41]
	v_mfma_f32_16x16x32_bf16 v[34:37], v[158:161], v[212:215], v[34:37]
	v_mfma_f32_16x16x32_bf16 v[14:17], v[150:153], v[232:235], v[14:17]
	v_mfma_f32_16x16x32_bf16 v[10:13], v[158:161], v[232:235], v[10:13]
	v_mfma_f32_16x16x32_bf16 v[86:89], v[166:169], v[196:199], v[86:89]
	v_mfma_f32_16x16x32_bf16 v[82:85], v[174:177], v[196:199], v[82:85]
	v_mfma_f32_16x16x32_bf16 v[54:57], v[166:169], v[204:207], v[54:57]
	v_mfma_f32_16x16x32_bf16 v[50:53], v[174:177], v[204:207], v[50:53]
	v_mfma_f32_16x16x32_bf16 v[22:25], v[166:169], v[212:215], v[22:25]
	v_mfma_f32_16x16x32_bf16 v[18:21], v[174:177], v[212:215], v[18:21]
	v_mfma_f32_16x16x32_bf16 v[6:9], v[166:169], v[232:235], v[6:9]
	v_mfma_f32_16x16x32_bf16 v[2:5], v[174:177], v[232:235], v[2:5]
	s_setprio 0
	s_barrier
	s_add_i32 s67, s67, 2
	s_add_u32 s35, s35, 0x100
	s_addc_u32 s37, s37, 0
	s_cmp_gt_u32 s67, 41
	s_mov_b64 s[10:11], s[8:9]
	s_cbranch_scc0 .LBB0_1632
	s_and_b64 vcc, exec, s[20:21]
	s_cbranch_vccz .LBB0_1635
	s_barrier
